# baseline (speedup 1.0000x reference)
; DEVI float frsq_(float x) { return __builtin_amdgcn_rsqf(x); }
; #define STAGE(P,BASE,br,kt) do{ long _g=(long)(br)*K+(long)(kt)*BK; \
;     _Pragma("unroll") for(int _i=0;_i<2;++_i){ int _b=tid*16+_i*8192; int _r,_c; stage_rc<2>(_b,_r,_c); \
;       __builtin_amdgcn_global_load_lds((const unsigned*)(BASE+_g+(long)_r*K+_c), \
;         (__attribute__((address_space(3))) unsigned*)((char*)(P)+_b),16,0,0);} }while(0)
; #define WAIT_VN(n) asm volatile("s_waitcnt vmcnt(" #n ")":::"memory")
; #define BAR __builtin_amdgcn_s_barrier()
; template <int EPI, bool SWAP>
; DEVI void gemm_tile(const Params& p, char* shm_, const u16* __restrict__ A, const u16* __restrict__ Bt, int K, int brow, int bcol,
;                     float* rst, const EpiArgs& ea) {
;     ...
;   if (ea.ss != nullptr && tid < 256) rst[tid] = frsq_(ea.ss[brow + tid] * (1.f / DM) + EPS);
;   u16* shm = (u16*)shm_;
;     ...
;   const int wid=tid>>6,lane=tid&63,wr=wid>>2,wc=wid&3,fr=lane&15,fq=lane>>4;
;   f32x4 acc[8][4];
; #pragma unroll
;   for (int m = 0; m < 8; ++m)
; #pragma unroll
;     for (int n = 0; n < 4; ++n) acc[m][n] = f32x4{0.f, 0.f, 0.f, 0.f};
;   bf16x8 At[4][2],B0[2][2],B1[2][2];
;   const int nt=K/BK;
;   STAGE(SB(0,0),Bt,bcol,0); STAGE(SA(0,0),A,brow,0);
;   STAGE(SB(0,1),Bt,bcol+HALF,0); STAGE(SA(0,1),A,brow+HALF,0);
;   if(wr==1)BAR;
;   WAIT_VN(4); BAR;
;   STAGE(SB(1,0),Bt,bcol,1); STAGE(SA(1,0),A,brow,1); STAGE(SB(1,1),Bt,bcol+HALF,1);
;   WAIT_VN(6); BAR;
.LBB0_219:
	v_mov_b32_e32 v128, v220
	s_nop 0
	v_cmp_gt_i32_e32 vcc, s17, v128
	s_and_saveexec_b64 s[70:71], vcc
	s_cbranch_execz .LBB0_221
	v_add_u32_e32 v0, s52, v128
	v_ashrrev_i32_e32 v1, 31, v0
	v_lshl_add_u64 v[0:1], v[0:1], 2, s[6:7]
	global_load_dword v221, v[0:1], off
	v_lshl_add_u32 v223, v128, 2, s97
.LBB0_221:
	s_or_b64 exec, exec, s[70:71]
	v_lshlrev_b32_e32 v147, 4, v128
	v_and_b32_e32 v0, 32, v128
	v_bitop3_b32 v0, v147, v0, 48 bitop3:0x6c
	v_lshrrev_b32_e32 v12, 1, v0
	v_ashrrev_i32_e32 v14, 6, v128
	v_lshrrev_b32_e32 v0, 31, v128
	v_add_u32_e32 v1, v14, v0
	v_ashrrev_i32_e32 v15, 1, v1
	v_and_b32_e32 v1, 0x7fffffe, v1
	v_sub_u32_e32 v1, v14, v1
	v_lshl_or_b32 v2, v1, 5, v12
	v_add_u32_e32 v149, 0x2000, v147
	v_ashrrev_i32_e32 v3, 31, v2
	v_ashrrev_i32_e32 v17, 10, v149
	s_ashr_i32 s69, s68, 31
	v_bfe_u32 v13, v128, 2, 4
	v_lshlrev_b32_e32 v16, 4, v15
	v_lshlrev_b64 v[22:23], 1, v[2:3]
	v_lshrrev_b32_e32 v2, 31, v17
	s_lshl_b64 s[70:71], s[68:69], 11
	v_or_b32_e32 v0, v16, v13
	v_add_u32_e32 v3, v17, v2
	s_add_u32 s78, s74, s70
	v_ashrrev_i32_e32 v1, 31, v0
	v_ashrrev_i32_e32 v18, 1, v3
	s_addc_u32 s79, s75, s71
	v_lshlrev_b64 v[20:21], 11, v[0:1]
	v_add_u32_e32 v148, 0x10000, v147
	v_lshlrev_b32_e32 v19, 4, v18
	v_and_b32_e32 v3, 0x7fffffe, v3
	v_lshl_add_u64 v[0:1], s[78:79], 0, v[20:21]
	v_readfirstlane_b32 s53, v148
	v_or_b32_e32 v2, v19, v13
	v_sub_u32_e32 v3, v17, v3
	v_add_u32_e32 v154, 0x12000, v147
	v_lshl_add_u64 v[0:1], v[0:1], 0, v[22:23]
	s_mov_b32 m0, s53
	v_lshl_or_b32 v4, v3, 5, v12
	v_ashrrev_i32_e32 v3, 31, v2
	v_readfirstlane_b32 s53, v154
	global_load_lds_dwordx4 v[0:1], off
	v_lshlrev_b64 v[24:25], 11, v[2:3]
	s_mov_b32 m0, s53
	s_ashr_i32 s53, s52, 31
	v_lshl_add_u64 v[2:3], s[78:79], 0, v[24:25]
	s_lshl_b64 s[78:79], s[52:53], 11
	s_add_u32 s80, s38, s78
	v_ashrrev_i32_e32 v5, 31, v4
	s_addc_u32 s81, s39, s79
	v_lshlrev_b64 v[26:27], 1, v[4:5]
	v_lshl_add_u64 v[4:5], s[80:81], 0, v[20:21]
	v_lshl_add_u64 v[6:7], s[80:81], 0, v[24:25]
	s_or_b32 s80, s68, 0x80
	s_ashr_i32 s81, s80, 31
	s_lshl_b64 s[80:81], s[80:81], 11
	s_add_u32 s80, s74, s80
	s_addc_u32 s81, s75, s81
	v_lshl_add_u64 v[8:9], s[80:81], 0, v[20:21]
	v_lshl_add_u64 v[10:11], s[80:81], 0, v[24:25]
	s_or_b32 s80, s52, 0x80
	v_lshl_add_u64 v[2:3], v[2:3], 0, v[26:27]
	v_readfirstlane_b32 s53, v147
	s_ashr_i32 s81, s80, 31
	global_load_lds_dwordx4 v[2:3], off
	v_lshl_add_u64 v[4:5], v[4:5], 0, v[22:23]
	s_mov_b32 m0, s53
	v_readfirstlane_b32 s53, v149
	v_add_u32_e32 v156, 0x14000, v147
	s_lshl_b64 s[80:81], s[80:81], 11
	global_load_lds_dwordx4 v[4:5], off
	v_lshl_add_u64 v[6:7], v[6:7], 0, v[26:27]
	s_mov_b32 m0, s53
	v_readfirstlane_b32 s53, v156
	v_add_u32_e32 v157, 0x16000, v147
	s_add_u32 s80, s38, s80
	global_load_lds_dwordx4 v[6:7], off
	v_lshl_add_u64 v[8:9], v[8:9], 0, v[22:23]
	s_mov_b32 m0, s53
	v_readfirstlane_b32 s53, v157
	s_addc_u32 s81, s39, s81
	v_add_u32_e32 v159, 0x4000, v147
	global_load_lds_dwordx4 v[8:9], off
	v_lshl_add_u64 v[10:11], v[10:11], 0, v[26:27]
	s_mov_b32 m0, s53
	v_lshl_add_u64 v[20:21], s[80:81], 0, v[20:21]
	v_readfirstlane_b32 s53, v159
	v_add_u32_e32 v160, 0x6000, v147
	global_load_lds_dwordx4 v[10:11], off
	v_lshl_add_u64 v[130:131], v[20:21], 0, v[22:23]
	s_mov_b32 m0, s53
	v_lshl_add_u64 v[20:21], s[80:81], 0, v[24:25]
	v_readfirstlane_b32 s53, v160
	global_load_lds_dwordx4 v[130:131], off
	v_lshl_add_u64 v[132:133], v[20:21], 0, v[26:27]
	s_mov_b32 m0, s53
	v_ashrrev_i32_e32 v20, 8, v128
	global_load_lds_dwordx4 v[132:133], off
	v_cmp_eq_u32_e32 vcc, 1, v20
	s_and_saveexec_b64 s[80:81], vcc
	s_cbranch_execz .LBB0_223
	s_barrier
; #define STAGE(P,BASE,br,kt) do{ long _g=(long)(br)*K+(long)(kt)*BK; \
;     _Pragma("unroll") for(int _i=0;_i<2;++_i){ int _b=tid*16+_i*8192; int _r,_c; stage_rc<2>(_b,_r,_c); \
;       __builtin_amdgcn_global_load_lds((const unsigned*)(BASE+_g+(long)_r*K+_c), \
;         (__attribute__((address_space(3))) unsigned*)((char*)(P)+_b),16,0,0);} }while(0)
; #define WAIT_VN(n) asm volatile("s_waitcnt vmcnt(" #n ")":::"memory")
; #define BAR __builtin_amdgcn_s_barrier()
; template <int EPI, bool SWAP>
; DEVI void gemm_tile(const Params& p, char* shm_, const u16* __restrict__ A, const u16* __restrict__ Bt, int K, int brow, int bcol,
;                     float* rst, const EpiArgs& ea) {
;     ...
;   f32x4 acc[8][4];
; #pragma unroll
;   for (int m = 0; m < 8; ++m)
; #pragma unroll
;     for (int n = 0; n < 4; ++n) acc[m][n] = f32x4{0.f, 0.f, 0.f, 0.f};
;   bf16x8 At[4][2],B0[2][2],B1[2][2];
;   const int nt=K/BK;
;   STAGE(SB(0,0),Bt,bcol,0); STAGE(SA(0,0),A,brow,0);
;   STAGE(SB(0,1),Bt,bcol+HALF,0); STAGE(SA(0,1),A,brow+HALF,0);
;   if(wr==1)BAR;
;   WAIT_VN(4); BAR;
;   STAGE(SB(1,0),Bt,bcol,1); STAGE(SA(1,0),A,brow,1); STAGE(SB(1,1),Bt,bcol+HALF,1);
;   WAIT_VN(6); BAR;
.LBB0_223:
	s_or_b64 exec, exec, s[80:81]
	v_add_u32_e32 v161, 0x18000, v147
	v_add_u32_e32 v162, 0x1a000, v147
	v_readfirstlane_b32 s53, v161
	v_lshl_add_u64 v[0:1], v[0:1], 0, s[10:11]
	s_mov_b32 m0, s53
	v_readfirstlane_b32 s53, v162
	v_add_u32_e32 v163, 0x8000, v147
	s_waitcnt vmcnt(4)
	s_barrier
	global_load_lds_dwordx4 v[0:1], off
	v_lshl_add_u64 v[0:1], v[2:3], 0, s[10:11]
	s_mov_b32 m0, s53
	v_readfirstlane_b32 s53, v163
	v_add_u32_e32 v164, 0xa000, v147
	global_load_lds_dwordx4 v[0:1], off
	v_lshl_add_u64 v[0:1], v[4:5], 0, s[10:11]
	s_mov_b32 m0, s53
	v_readfirstlane_b32 s53, v164
	v_add_u32_e32 v165, 0x1c000, v147
	global_load_lds_dwordx4 v[0:1], off
	v_lshl_add_u64 v[0:1], v[6:7], 0, s[10:11]
	s_mov_b32 m0, s53
	v_readfirstlane_b32 s53, v165
	v_add_u32_e32 v166, 0x1e000, v147
	global_load_lds_dwordx4 v[0:1], off
	v_lshl_add_u64 v[0:1], v[8:9], 0, s[10:11]
	s_mov_b32 m0, s53
	v_readfirstlane_b32 s53, v166
	global_load_lds_dwordx4 v[0:1], off
	v_lshl_add_u64 v[0:1], v[10:11], 0, s[10:11]
	s_mov_b32 m0, s53
	v_and_b32_e32 v21, 15, v128
	global_load_lds_dwordx4 v[0:1], off
	v_lshlrev_b32_e32 v2, 2, v128
	v_and_b32_e32 v22, 48, v128
	v_lshlrev_b32_e32 v0, 6, v21
	v_and_b32_e32 v2, 32, v2
	v_or_b32_e32 v1, v0, v22
	v_bitop3_b32 v11, v0, v2, v22 bitop3:0x36
	v_lshlrev_b32_e32 v0, 6, v128
	v_and_b32_e32 v0, 0x3c0, v0
	v_bitop3_b32 v22, v0, v2, v22 bitop3:0x36
	v_add_u32_e32 v0, v16, v13
	v_lshl_or_b32 v4, v14, 5, v12
	v_lshlrev_b32_e32 v5, 6, v15
	v_bitop3_b32 v21, v1, s45, v2 bitop3:0xde
	v_bitop3_b32 v23, v1, s82, v2 bitop3:0xde
	v_bitop3_b32 v24, v1, s83, v2 bitop3:0xde
	v_bitop3_b32 v25, v1, s84, v2 bitop3:0xde
	v_ashrrev_i32_e32 v1, 31, v0
	v_sub_u32_e32 v4, v4, v5
	v_lshlrev_b64 v[0:1], 11, v[0:1]
	v_ashrrev_i32_e32 v5, 31, v4
	v_lshl_add_u64 v[2:3], s[70:71], 0, v[0:1]
	v_lshlrev_b64 v[4:5], 1, v[4:5]
	v_lshl_add_u64 v[134:135], v[2:3], 0, v[4:5]
	v_add_u32_e32 v2, v19, v13
	v_lshl_or_b32 v8, v17, 5, v12
	v_lshlrev_b32_e32 v9, 6, v18
	v_ashrrev_i32_e32 v3, 31, v2
	v_sub_u32_e32 v8, v8, v9
	v_lshlrev_b64 v[2:3], 11, v[2:3]
	v_ashrrev_i32_e32 v9, 31, v8
	v_lshl_add_u64 v[0:1], s[78:79], 0, v[0:1]
	v_bfe_u32 v145, v128, 6, 2
	s_waitcnt vmcnt(6)
	v_lshlrev_b32_e32 v146, 6, v20
	v_lshlrev_b32_e32 v20, 13, v20
	v_lshlrev_b64 v[8:9], 1, v[8:9]
	v_lshl_add_u64 v[138:139], v[0:1], 0, v[4:5]
	v_lshl_add_u64 v[0:1], s[78:79], 0, v[2:3]
	v_lshlrev_b32_e32 v10, 12, v145
	v_or_b32_e32 v26, 0x800, v20
	v_or_b32_e32 v27, 0x1000, v20
	v_or_b32_e32 v28, 0x1800, v20
	v_lshl_add_u64 v[6:7], s[70:71], 0, v[2:3]
	v_lshl_add_u64 v[140:141], v[0:1], 0, v[8:9]
	v_mov_b32_e32 v0, 0
	v_lshl_add_u64 v[136:137], v[6:7], 0, v[8:9]
	s_mov_b32 s53, -2
	v_add_u32_e32 v170, v21, v10
	v_add_u32_e32 v153, v11, v20
	v_add_u32_e32 v152, v22, v26
	v_add_u32_e32 v151, v22, v27
	v_add_u32_e32 v150, v22, v28
	v_add_u32_e32 v169, 0xc000, v147
	v_add_u32_e32 v168, 0xe000, v147
	v_add_u32_e32 v167, v23, v10
	v_add_u32_e32 v158, v24, v10
	v_add_u32_e32 v155, v25, v10
	v_mov_b32_e32 v1, v0
	v_mov_b32_e32 v2, v0
	v_mov_b32_e32 v3, v0
	v_mov_b32_e32 v4, v0
	v_mov_b32_e32 v5, v0
	v_mov_b32_e32 v6, v0
	v_mov_b32_e32 v7, v0
	v_mov_b32_e32 v12, v0
	v_mov_b32_e32 v13, v0
	v_mov_b32_e32 v14, v0
	v_mov_b32_e32 v15, v0
	v_mov_b32_e32 v20, v0
	v_mov_b32_e32 v21, v0
	v_mov_b32_e32 v22, v0
	v_mov_b32_e32 v23, v0
	v_mov_b32_e32 v8, v0
	v_mov_b32_e32 v9, v0
	v_mov_b32_e32 v10, v0
	v_mov_b32_e32 v11, v0
	v_mov_b32_e32 v16, v0
	v_mov_b32_e32 v17, v0
	v_mov_b32_e32 v18, v0
	v_mov_b32_e32 v19, v0
	v_mov_b32_e32 v28, v0
	v_mov_b32_e32 v29, v0
	v_mov_b32_e32 v30, v0
	v_mov_b32_e32 v31, v0
	v_mov_b32_e32 v36, v0
	v_mov_b32_e32 v37, v0
	v_mov_b32_e32 v38, v0
	v_mov_b32_e32 v39, v0
	v_mov_b32_e32 v24, v0
	v_mov_b32_e32 v25, v0
	v_mov_b32_e32 v26, v0
	v_mov_b32_e32 v27, v0
	v_mov_b32_e32 v32, v0
	v_mov_b32_e32 v33, v0
	v_mov_b32_e32 v34, v0
	v_mov_b32_e32 v35, v0
	v_mov_b32_e32 v44, v0
	v_mov_b32_e32 v45, v0
	v_mov_b32_e32 v46, v0
	v_mov_b32_e32 v47, v0
	v_mov_b32_e32 v52, v0
	v_mov_b32_e32 v53, v0
	v_mov_b32_e32 v54, v0
	v_mov_b32_e32 v55, v0
	v_mov_b32_e32 v40, v0
	v_mov_b32_e32 v41, v0
	v_mov_b32_e32 v42, v0
	v_mov_b32_e32 v43, v0
	v_mov_b32_e32 v48, v0
	v_mov_b32_e32 v49, v0
	v_mov_b32_e32 v50, v0
	v_mov_b32_e32 v51, v0
	v_mov_b32_e32 v56, v0
	v_mov_b32_e32 v57, v0
	v_mov_b32_e32 v58, v0
	v_mov_b32_e32 v59, v0
	v_mov_b32_e32 v60, v0
	v_mov_b32_e32 v61, v0
	v_mov_b32_e32 v62, v0
	v_mov_b32_e32 v63, v0
	v_mov_b32_e32 v64, v0
	v_mov_b32_e32 v65, v0
	v_mov_b32_e32 v66, v0
	v_mov_b32_e32 v67, v0
	v_mov_b32_e32 v68, v0
	v_mov_b32_e32 v69, v0
	v_mov_b32_e32 v70, v0
	v_mov_b32_e32 v71, v0
	v_mov_b32_e32 v80, v0
	v_mov_b32_e32 v81, v0
	v_mov_b32_e32 v82, v0
	v_mov_b32_e32 v83, v0
	v_mov_b32_e32 v88, v0
	v_mov_b32_e32 v89, v0
	v_mov_b32_e32 v90, v0
	v_mov_b32_e32 v91, v0
	v_mov_b32_e32 v72, v0
	v_mov_b32_e32 v73, v0
	v_mov_b32_e32 v74, v0
	v_mov_b32_e32 v75, v0
	v_mov_b32_e32 v76, v0
	v_mov_b32_e32 v77, v0
	v_mov_b32_e32 v78, v0
	v_mov_b32_e32 v79, v0
	v_mov_b32_e32 v96, v0
	v_mov_b32_e32 v97, v0
	v_mov_b32_e32 v98, v0
	v_mov_b32_e32 v99, v0
	v_mov_b32_e32 v104, v0
	v_mov_b32_e32 v105, v0
	v_mov_b32_e32 v106, v0
	v_mov_b32_e32 v107, v0
	v_mov_b32_e32 v84, v0
	v_mov_b32_e32 v85, v0
	v_mov_b32_e32 v86, v0
	v_mov_b32_e32 v87, v0
	v_mov_b32_e32 v92, v0
	v_mov_b32_e32 v93, v0
	v_mov_b32_e32 v94, v0
	v_mov_b32_e32 v95, v0
	v_mov_b32_e32 v112, v0
	v_mov_b32_e32 v113, v0
	v_mov_b32_e32 v114, v0
	v_mov_b32_e32 v115, v0
	v_mov_b32_e32 v116, v0
	v_mov_b32_e32 v117, v0
	v_mov_b32_e32 v118, v0
	v_mov_b32_e32 v119, v0
	v_mov_b32_e32 v100, v0
	v_mov_b32_e32 v101, v0
	v_mov_b32_e32 v102, v0
	v_mov_b32_e32 v103, v0
	v_mov_b32_e32 v108, v0
	v_mov_b32_e32 v109, v0
	v_mov_b32_e32 v110, v0
	v_mov_b32_e32 v111, v0
	v_mov_b32_e32 v120, v0
	v_mov_b32_e32 v121, v0
	v_mov_b32_e32 v122, v0
	v_mov_b32_e32 v123, v0
	v_mov_b32_e32 v124, v0
	v_mov_b32_e32 v125, v0
	v_mov_b32_e32 v126, v0
	v_mov_b32_e32 v127, v0
	s_movk_i32 s98, 0x100
	v_cmp_gt_u32_e64 s[100:101], s98, v220
	s_and_saveexec_b64 s[98:99], s[100:101]
	v_mul_f32_e32 v221, 0x3a800000, v221
	v_add_f32_e32 v221, 0x358637bd, v221
	v_rsq_f32_e32 v221, v221
	ds_write_b32 v223, v221
	s_or_b64 exec, exec, s[98:99]
	s_barrier

; DEVI float frsq_(float x) { return __builtin_amdgcn_rsqf(x); }
; #define STAGE(P,BASE,br,kt) do{ long _g=(long)(br)*K+(long)(kt)*BK; \
;     _Pragma("unroll") for(int _i=0;_i<2;++_i){ int _b=tid*16+_i*8192; int _r,_c; stage_rc<2>(_b,_r,_c); \
;       __builtin_amdgcn_global_load_lds((const unsigned*)(BASE+_g+(long)_r*K+_c), \
;         (__attribute__((address_space(3))) unsigned*)((char*)(P)+_b),16,0,0);} }while(0)
; #define BAR __builtin_amdgcn_s_barrier()
; template <int EPI, bool SWAP>
; DEVI void gemm_tile(const Params& p, char* shm_, const u16* __restrict__ A, const u16* __restrict__ Bt, int K, int brow, int bcol,
;                     float* rst, const EpiArgs& ea) {
;     ...
;   if (ea.ss != nullptr && tid < 256) rst[tid] = frsq_(ea.ss[brow + tid] * (1.f / DM) + EPS);
;   u16* shm = (u16*)shm_;
;     ...
;   const int wid=tid>>6,lane=tid&63,wr=wid>>2,wc=wid&3,fr=lane&15,fq=lane>>4;
;   f32x4 acc[8][4];
; #pragma unroll
;   for (int m = 0; m < 8; ++m)
; #pragma unroll
;     for (int n = 0; n < 4; ++n) acc[m][n] = f32x4{0.f, 0.f, 0.f, 0.f};
;   bf16x8 At[4][2],B0[2][2],B1[2][2];
;   const int nt=K/BK;
;   STAGE(SB(0,0),Bt,bcol,0); STAGE(SA(0,0),A,brow,0);
;   STAGE(SB(0,1),Bt,bcol+HALF,0); STAGE(SA(0,1),A,brow+HALF,0);
;   if(wr==1)BAR;
.LBB0_234:
	s_or_b64 exec, exec, s[70:71]
	v_lshlrev_b32_e32 v146, 4, v128
	v_and_b32_e32 v0, 32, v128
	v_bitop3_b32 v0, v146, v0, 48 bitop3:0x6c
	v_lshrrev_b32_e32 v16, 1, v0
	v_ashrrev_i32_e32 v18, 6, v128
	v_lshrrev_b32_e32 v0, 31, v128
	v_add_u32_e32 v0, v18, v0
	v_ashrrev_i32_e32 v19, 1, v0
	v_bfe_u32 v17, v128, 2, 4
	v_lshlrev_b32_e32 v20, 4, v19
	v_and_b32_e32 v0, 0x7fffffe, v0
	s_lshl_b32 s8, s8, 19
	v_or_b32_e32 v2, v20, v17
	v_sub_u32_e32 v0, v18, v0
	s_add_u32 s78, s74, s8
	v_lshl_or_b32 v0, v0, 5, v16
	v_ashrrev_i32_e32 v3, 31, v2
	s_addc_u32 s79, s75, 0
	v_lshlrev_b64 v[2:3], 11, v[2:3]
	v_ashrrev_i32_e32 v1, 31, v0
	v_add_u32_e32 v148, 0x2000, v146
	v_lshl_add_u64 v[4:5], s[78:79], 0, v[2:3]
	v_lshlrev_b64 v[24:25], 1, v[0:1]
	v_ashrrev_i32_e32 v21, 10, v148
	v_lshl_add_u64 v[8:9], v[4:5], 0, v[24:25]
	v_lshrrev_b32_e32 v4, 31, v21
	v_add_u32_e32 v147, 0x10000, v146
	v_add_u32_e32 v4, v21, v4
	v_readfirstlane_b32 s53, v147
	v_ashrrev_i32_e32 v22, 1, v4
	v_add_u32_e32 v153, 0x12000, v146
	s_mov_b32 m0, s53
	v_lshlrev_b32_e32 v23, 4, v22
	v_and_b32_e32 v4, 0x7fffffe, v4
	v_readfirstlane_b32 s53, v153
	global_load_lds_dwordx4 v[8:9], off
	v_or_b32_e32 v6, v23, v17
	v_sub_u32_e32 v4, v21, v4
	s_mov_b32 m0, s53
	s_ashr_i32 s53, s52, 31
	v_lshl_or_b32 v4, v4, 5, v16
	v_ashrrev_i32_e32 v7, 31, v6
	s_lshl_b64 s[70:71], s[52:53], 11
	v_lshlrev_b64 v[6:7], 11, v[6:7]
	v_ashrrev_i32_e32 v5, 31, v4
	s_add_u32 s80, s38, s70
	v_lshl_add_u64 v[10:11], s[78:79], 0, v[6:7]
	v_lshlrev_b64 v[26:27], 1, v[4:5]
	s_addc_u32 s81, s39, s71
	v_lshl_add_u64 v[10:11], v[10:11], 0, v[26:27]
	v_lshl_add_u64 v[12:13], s[80:81], 0, v[2:3]
	v_readfirstlane_b32 s53, v146
	v_lshl_add_u64 v[14:15], s[80:81], 0, v[6:7]
	s_add_u32 s80, s78, 0x40000
	global_load_lds_dwordx4 v[10:11], off
	v_lshl_add_u64 v[12:13], v[12:13], 0, v[24:25]
	s_mov_b32 m0, s53
	v_readfirstlane_b32 s53, v148
	s_addc_u32 s81, s79, 0
	v_add_u32_e32 v155, 0x14000, v146
	global_load_lds_dwordx4 v[12:13], off
	v_lshl_add_u64 v[14:15], v[14:15], 0, v[26:27]
	s_mov_b32 m0, s53
	v_lshl_add_u64 v[28:29], s[80:81], 0, v[2:3]
	v_readfirstlane_b32 s53, v155
	global_load_lds_dwordx4 v[14:15], off
	v_lshl_add_u64 v[28:29], v[28:29], 0, v[24:25]
	s_mov_b32 m0, s53
	v_add_u32_e32 v156, 0x16000, v146
	global_load_lds_dwordx4 v[28:29], off
	v_lshl_add_u64 v[28:29], s[80:81], 0, v[6:7]
	s_or_b32 s80, s52, 0x80
	s_ashr_i32 s81, s80, 31
	s_lshl_b64 s[80:81], s[80:81], 11
	v_readfirstlane_b32 s53, v156
	s_add_u32 s80, s38, s80
	v_lshl_add_u64 v[28:29], v[28:29], 0, v[26:27]
	s_mov_b32 m0, s53
	s_addc_u32 s81, s39, s81
	v_add_u32_e32 v158, 0x4000, v146
	global_load_lds_dwordx4 v[28:29], off
	v_lshl_add_u64 v[28:29], s[80:81], 0, v[2:3]
	v_readfirstlane_b32 s53, v158
	v_add_u32_e32 v159, 0x6000, v146
	v_lshl_add_u64 v[130:131], v[28:29], 0, v[24:25]
	s_mov_b32 m0, s53
	v_lshl_add_u64 v[24:25], s[80:81], 0, v[6:7]
	v_readfirstlane_b32 s53, v159
	global_load_lds_dwordx4 v[130:131], off
	v_lshl_add_u64 v[132:133], v[24:25], 0, v[26:27]
	s_mov_b32 m0, s53
	v_ashrrev_i32_e32 v24, 8, v128
	global_load_lds_dwordx4 v[132:133], off
	v_cmp_eq_u32_e32 vcc, 1, v24
	s_and_saveexec_b64 s[80:81], vcc
	s_cbranch_execz .LBB0_236
	s_barrier
; #define STAGE(P,BASE,br,kt) do{ long _g=(long)(br)*K+(long)(kt)*BK; \
;     _Pragma("unroll") for(int _i=0;_i<2;++_i){ int _b=tid*16+_i*8192; int _r,_c; stage_rc<2>(_b,_r,_c); \
;       __builtin_amdgcn_global_load_lds((const unsigned*)(BASE+_g+(long)_r*K+_c), \
;         (__attribute__((address_space(3))) unsigned*)((char*)(P)+_b),16,0,0);} }while(0)
; #define WAIT_VN(n) asm volatile("s_waitcnt vmcnt(" #n ")":::"memory")
; #define BAR __builtin_amdgcn_s_barrier()
; template <int EPI, bool SWAP>
; DEVI void gemm_tile(const Params& p, char* shm_, const u16* __restrict__ A, const u16* __restrict__ Bt, int K, int brow, int bcol,
;                     float* rst, const EpiArgs& ea) {
;     ...
;   f32x4 acc[8][4];
; #pragma unroll
;   for (int m = 0; m < 8; ++m)
; #pragma unroll
;     for (int n = 0; n < 4; ++n) acc[m][n] = f32x4{0.f, 0.f, 0.f, 0.f};
;   bf16x8 At[4][2],B0[2][2],B1[2][2];
;   const int nt=K/BK;
;   STAGE(SB(0,0),Bt,bcol,0); STAGE(SA(0,0),A,brow,0);
;   STAGE(SB(0,1),Bt,bcol+HALF,0); STAGE(SA(0,1),A,brow+HALF,0);
;   if(wr==1)BAR;
;   WAIT_VN(4); BAR;
;   STAGE(SB(1,0),Bt,bcol,1); STAGE(SA(1,0),A,brow,1); STAGE(SB(1,1),Bt,bcol+HALF,1);
;   WAIT_VN(6); BAR;
.LBB0_236:
	s_or_b64 exec, exec, s[80:81]
	v_add_u32_e32 v160, 0x18000, v146
	v_add_u32_e32 v161, 0x1a000, v146
	v_readfirstlane_b32 s53, v160
	v_lshl_add_u64 v[8:9], v[8:9], 0, s[10:11]
	s_mov_b32 m0, s53
	v_readfirstlane_b32 s53, v161
	v_add_u32_e32 v162, 0x8000, v146
	s_waitcnt vmcnt(4)
	s_barrier
	global_load_lds_dwordx4 v[8:9], off
	v_lshl_add_u64 v[8:9], v[10:11], 0, s[10:11]
	s_mov_b32 m0, s53
	v_readfirstlane_b32 s53, v162
	v_add_u32_e32 v163, 0xa000, v146
	s_add_u32 s78, s78, 0x40080
	global_load_lds_dwordx4 v[8:9], off
	v_lshl_add_u64 v[8:9], v[12:13], 0, s[10:11]
	s_mov_b32 m0, s53
	v_readfirstlane_b32 s53, v163
	s_addc_u32 s79, s79, 0
	v_add_u32_e32 v164, 0x1c000, v146
	global_load_lds_dwordx4 v[8:9], off
	v_lshl_add_u64 v[8:9], v[14:15], 0, s[10:11]
	s_mov_b32 m0, s53
	v_lshl_add_u64 v[2:3], s[78:79], 0, v[2:3]
	v_readfirstlane_b32 s53, v164
	global_load_lds_dwordx4 v[8:9], off
	v_lshl_add_u64 v[0:1], v[0:1], 1, v[2:3]
	s_mov_b32 m0, s53
	v_add_u32_e32 v165, 0x1e000, v146
	global_load_lds_dwordx4 v[0:1], off
	v_lshl_add_u64 v[0:1], s[78:79], 0, v[6:7]
	v_readfirstlane_b32 s53, v165
	v_lshl_add_u64 v[0:1], v[4:5], 1, v[0:1]
	s_mov_b32 m0, s53
	v_and_b32_e32 v25, 15, v128
	global_load_lds_dwordx4 v[0:1], off
	v_and_b32_e32 v26, 48, v128
	v_lshlrev_b32_e32 v0, 6, v128
	v_lshlrev_b32_e32 v1, 6, v25
	v_lshlrev_b32_e32 v3, 2, v128
	v_and_b32_e32 v6, 0x3000, v0
	v_or_b32_e32 v2, v1, v26
	v_and_b32_e32 v3, 32, v3
	v_and_b32_e32 v0, 0x3c0, v0
	v_bitop3_b32 v7, v1, v3, v26 bitop3:0x36
	v_bitop3_b32 v8, v2, s45, v3 bitop3:0xde
	v_bitop3_b32 v9, v2, s82, v3 bitop3:0xde
	v_bitop3_b32 v10, v2, s83, v3 bitop3:0xde
	v_bitop3_b32 v11, v2, s84, v3 bitop3:0xde
	v_bitop3_b32 v13, v0, v3, v26 bitop3:0x36
	v_add_u32_e32 v0, v20, v17
	v_lshl_or_b32 v2, v18, 5, v16
	v_lshlrev_b32_e32 v3, 6, v19
	v_ashrrev_i32_e32 v1, 31, v0
	v_sub_u32_e32 v2, v2, v3
	v_lshlrev_b64 v[0:1], 11, v[0:1]
	v_ashrrev_i32_e32 v3, 31, v2
	v_lshl_add_u64 v[0:1], v[2:3], 1, v[0:1]
	v_add_u32_e32 v2, v23, v17
	v_lshl_or_b32 v4, v21, 5, v16
	v_lshlrev_b32_e32 v5, 6, v22
	v_ashrrev_i32_e32 v3, 31, v2
	v_sub_u32_e32 v4, v4, v5
	s_waitcnt vmcnt(6)
	v_lshlrev_b32_e32 v12, 13, v24
	v_lshlrev_b64 v[2:3], 11, v[2:3]
	v_ashrrev_i32_e32 v5, 31, v4
	v_lshlrev_b32_e32 v145, 6, v24
	v_or_b32_e32 v14, 0x800, v12
	v_or_b32_e32 v15, 0x1000, v12
	v_or_b32_e32 v24, 0x1800, v12
	v_lshl_add_u64 v[134:135], v[0:1], 0, s[8:9]
	v_lshl_add_u64 v[2:3], v[4:5], 1, v[2:3]
	v_lshl_add_u64 v[138:139], v[0:1], 0, s[70:71]
	v_mov_b32_e32 v0, 0
	v_lshl_add_u64 v[136:137], v[2:3], 0, s[8:9]
	v_lshl_add_u64 v[140:141], v[2:3], 0, s[70:71]
	s_mov_b32 s8, -2
	v_add_u32_e32 v167, v8, v6
	v_add_u32_e32 v152, v7, v12
	v_add_u32_e32 v151, v13, v14
	v_add_u32_e32 v150, v13, v15
	v_add_u32_e32 v149, v13, v24
	v_add_u32_e32 v166, v9, v6
	v_add_u32_e32 v157, v10, v6
	v_add_u32_e32 v154, v11, v6
	v_mov_b32_e32 v1, v0
	v_mov_b32_e32 v2, v0
	v_mov_b32_e32 v3, v0
	v_mov_b32_e32 v4, v0
	v_mov_b32_e32 v5, v0
	v_mov_b32_e32 v6, v0
	v_mov_b32_e32 v7, v0
	v_mov_b32_e32 v12, v0
	v_mov_b32_e32 v13, v0
	v_mov_b32_e32 v14, v0
	v_mov_b32_e32 v15, v0
	v_mov_b32_e32 v20, v0
	v_mov_b32_e32 v21, v0
	v_mov_b32_e32 v22, v0
	v_mov_b32_e32 v23, v0
	v_mov_b32_e32 v8, v0
	v_mov_b32_e32 v9, v0
	v_mov_b32_e32 v10, v0
	v_mov_b32_e32 v11, v0
	v_mov_b32_e32 v16, v0
	v_mov_b32_e32 v17, v0
	v_mov_b32_e32 v18, v0
	v_mov_b32_e32 v19, v0
	v_mov_b32_e32 v28, v0
	v_mov_b32_e32 v29, v0
	v_mov_b32_e32 v30, v0
	v_mov_b32_e32 v31, v0
	v_mov_b32_e32 v36, v0
	v_mov_b32_e32 v37, v0
	v_mov_b32_e32 v38, v0
	v_mov_b32_e32 v39, v0
	v_mov_b32_e32 v24, v0
	v_mov_b32_e32 v25, v0
	v_mov_b32_e32 v26, v0
	v_mov_b32_e32 v27, v0
	v_mov_b32_e32 v32, v0
	v_mov_b32_e32 v33, v0
	v_mov_b32_e32 v34, v0
	v_mov_b32_e32 v35, v0
	v_mov_b32_e32 v44, v0
	v_mov_b32_e32 v45, v0
	v_mov_b32_e32 v46, v0
	v_mov_b32_e32 v47, v0
	v_mov_b32_e32 v52, v0
	v_mov_b32_e32 v53, v0
	v_mov_b32_e32 v54, v0
	v_mov_b32_e32 v55, v0
	v_mov_b32_e32 v40, v0
	v_mov_b32_e32 v41, v0
	v_mov_b32_e32 v42, v0
	v_mov_b32_e32 v43, v0
	v_mov_b32_e32 v48, v0
	v_mov_b32_e32 v49, v0
	v_mov_b32_e32 v50, v0
	v_mov_b32_e32 v51, v0
	v_mov_b32_e32 v56, v0
	v_mov_b32_e32 v57, v0
	v_mov_b32_e32 v58, v0
	v_mov_b32_e32 v59, v0
	v_mov_b32_e32 v60, v0
	v_mov_b32_e32 v61, v0
	v_mov_b32_e32 v62, v0
	v_mov_b32_e32 v63, v0
	v_mov_b32_e32 v64, v0
	v_mov_b32_e32 v65, v0
	v_mov_b32_e32 v66, v0
	v_mov_b32_e32 v67, v0
	v_mov_b32_e32 v68, v0
	v_mov_b32_e32 v69, v0
	v_mov_b32_e32 v70, v0
	v_mov_b32_e32 v71, v0
	v_mov_b32_e32 v80, v0
	v_mov_b32_e32 v81, v0
	v_mov_b32_e32 v82, v0
	v_mov_b32_e32 v83, v0
	v_mov_b32_e32 v88, v0
	v_mov_b32_e32 v89, v0
	v_mov_b32_e32 v90, v0
	v_mov_b32_e32 v91, v0
	v_mov_b32_e32 v72, v0
	v_mov_b32_e32 v73, v0
	v_mov_b32_e32 v74, v0
	v_mov_b32_e32 v75, v0
	v_mov_b32_e32 v76, v0
	v_mov_b32_e32 v77, v0
	v_mov_b32_e32 v78, v0
	v_mov_b32_e32 v79, v0
	v_mov_b32_e32 v96, v0
	v_mov_b32_e32 v97, v0
	v_mov_b32_e32 v98, v0
	v_mov_b32_e32 v99, v0
	v_mov_b32_e32 v104, v0
	v_mov_b32_e32 v105, v0
	v_mov_b32_e32 v106, v0
	v_mov_b32_e32 v107, v0
	v_mov_b32_e32 v84, v0
	v_mov_b32_e32 v85, v0
	v_mov_b32_e32 v86, v0
	v_mov_b32_e32 v87, v0
	v_mov_b32_e32 v92, v0
	v_mov_b32_e32 v93, v0
	v_mov_b32_e32 v94, v0
	v_mov_b32_e32 v95, v0
	v_mov_b32_e32 v112, v0
	v_mov_b32_e32 v113, v0
	v_mov_b32_e32 v114, v0
	v_mov_b32_e32 v115, v0
	v_mov_b32_e32 v116, v0
	v_mov_b32_e32 v117, v0
	v_mov_b32_e32 v118, v0
	v_mov_b32_e32 v119, v0
	v_mov_b32_e32 v100, v0
	v_mov_b32_e32 v101, v0
	v_mov_b32_e32 v102, v0
	v_mov_b32_e32 v103, v0
	v_mov_b32_e32 v108, v0
	v_mov_b32_e32 v109, v0
	v_mov_b32_e32 v110, v0
	v_mov_b32_e32 v111, v0
	v_mov_b32_e32 v120, v0
	v_mov_b32_e32 v121, v0
	v_mov_b32_e32 v122, v0
	v_mov_b32_e32 v123, v0
	v_mov_b32_e32 v124, v0
	v_mov_b32_e32 v125, v0
	v_mov_b32_e32 v126, v0
	v_mov_b32_e32 v127, v0
	s_movk_i32 s98, 0x100
	v_cmp_gt_u32_e64 s[100:101], s98, v220
	s_and_saveexec_b64 s[98:99], s[100:101]
	v_mul_f32_e32 v221, 0x3a800000, v221
	v_add_f32_e32 v221, 0x358637bd, v221
	v_rsq_f32_e32 v221, v221
	ds_write_b32 v223, v221
	s_or_b64 exec, exec, s[98:99]
	s_barrier

; #define STAGE(P,BASE,br,kt) do{ long _g=(long)(br)*K+(long)(kt)*BK; \
;     _Pragma("unroll") for(int _i=0;_i<2;++_i){ int _b=tid*16+_i*8192; int _r,_c; stage_rc<2>(_b,_r,_c); \
;       __builtin_amdgcn_global_load_lds((const unsigned*)(BASE+_g+(long)_r*K+_c), \
;         (__attribute__((address_space(3))) unsigned*)((char*)(P)+_b),16,0,0);} }while(0)
; #define BAR __builtin_amdgcn_s_barrier()
; template <int EPI, bool SWAP>
; DEVI void gemm_tile(const Params& p, char* shm_, const u16* __restrict__ A, const u16* __restrict__ Bt, int K, int brow, int bcol,
;                     float* rst, const EpiArgs& ea) {
;     ...
;   STAGE(SB(0,0),Bt,bcol,0); STAGE(SA(0,0),A,brow,0);
;   STAGE(SB(0,1),Bt,bcol+HALF,0); STAGE(SA(0,1),A,brow+HALF,0);
;   if(wr==1)BAR;
; template <int EPI>
; DEVI void gemm_phase(const Params& p, char* shm, const u16* __restrict__ A, const u16* __restrict__ Bt, int N, int K, const EpiArgs& ea) {
;     ...
;   for (int t = blockIdx.x; t < nwg; t += gridDim.x) {
;     float* rst = rsS + par * 256; par ^= 1;
;     int wgid = t;
;     { int q = nwg / NXCD, r = nwg % NXCD, xcd = wgid % NXCD, off = wgid / NXCD;
;       wgid = (xcd < r ? xcd * (q + 1) : r * (q + 1) + (xcd - r) * q) + off; }
;     int nig = WGM * nN, gid = wgid / nig, fm = gid * WGM, gsz = min(nM - fm, WGM);
;     int pm = fm + ((wgid % nig) % gsz), pn = (wgid % nig) / gsz, brow = pm * BM, bcol = pn * BM;
;     if constexpr (EPI == EPI_HG_IN) gemm_tile<EPI, false>(p, shm, A, Bt, K, brow, bcol, rst, ea);
;     else if constexpr (EPI == EPI_FOX_IN) {
;       if (tile_swap<EPI>(bcol)) gemm_tile<EPI, true>(p, shm, A, Bt, K, brow, bcol, rst, ea);
;       else gemm_tile<EPI, false>(p, shm, A, Bt, K, brow, bcol, rst, ea);
;     } else gemm_tile<EPI, true>(p, shm, A, Bt, K, brow, bcol, rst, ea);
.LBB0_373:
	s_ashr_i32 s4, s16, 3
	s_add_i32 s4, s92, s4
	s_ashr_i32 s5, s4, 31
	s_lshr_b32 s5, s5, 27
	s_add_i32 s5, s4, s5
	s_and_b32 s16, s5, 0xffe0
	s_sub_i32 s4, s4, s16
	s_bfe_i32 s16, s4, 0x80000
	s_bfe_u32 s16, s16, 0x3000c
	v_mov_b32_e32 v128, v220
	s_add_i32 s16, s4, s16
	s_bfe_i32 s17, s16, 0x80000
	v_lshlrev_b32_e32 v145, 4, v128
	v_and_b32_e32 v0, 32, v128
	s_and_b32 s16, s16, 0xf8
	v_bitop3_b32 v0, v145, v0, 48 bitop3:0x6c
	s_sub_i32 s4, s4, s16
	v_lshrrev_b32_e32 v12, 1, v0
	v_ashrrev_i32_e32 v14, 6, v128
	v_lshrrev_b32_e32 v0, 31, v128
	s_sext_i32_i8 s4, s4
	s_lshl_b32 s5, s5, 6
	s_waitcnt lgkmcnt(0)
	v_add_u32_e32 v1, v14, v0
	s_sext_i32_i16 s17, s17
	s_and_b32 s5, s5, 0xfffff800
	s_lshl_b32 s4, s4, 8
	v_ashrrev_i32_e32 v15, 1, v1
	v_and_b32_e32 v1, 0x7fffffe, v1
	s_add_i32 s4, s4, s5
	s_lshl_b32 s5, s17, 5
	v_sub_u32_e32 v1, v14, v1
	s_and_b32 s92, s5, 0xffffff00
	v_lshl_or_b32 v2, v1, 5, v12
	v_add_u32_e32 v147, 0x2000, v145
	s_ashr_i32 s93, s92, 31
	v_bfe_u32 v13, v128, 2, 4
	v_lshlrev_b32_e32 v16, 4, v15
	v_ashrrev_i32_e32 v3, 31, v2
	v_ashrrev_i32_e32 v17, 10, v147
	s_lshl_b64 s[94:95], s[92:93], 11
	v_or_b32_e32 v0, v16, v13
	v_lshlrev_b64 v[22:23], 1, v[2:3]
	v_lshrrev_b32_e32 v2, 31, v17
	s_add_u32 s16, s12, s94
	v_ashrrev_i32_e32 v1, 31, v0
	v_add_u32_e32 v3, v17, v2
	s_addc_u32 s17, s13, s95
	v_lshlrev_b64 v[20:21], 11, v[0:1]
	v_add_u32_e32 v146, 0x10000, v145
	v_ashrrev_i32_e32 v18, 1, v3
	v_lshl_add_u64 v[0:1], s[16:17], 0, v[20:21]
	v_readfirstlane_b32 s5, v146
	v_lshlrev_b32_e32 v19, 4, v18
	v_and_b32_e32 v3, 0x7fffffe, v3
	v_add_u32_e32 v152, 0x12000, v145
	v_lshl_add_u64 v[0:1], v[0:1], 0, v[22:23]
	s_mov_b32 m0, s5
	v_or_b32_e32 v2, v19, v13
	v_sub_u32_e32 v3, v17, v3
	v_readfirstlane_b32 s5, v152
	global_load_lds_dwordx4 v[0:1], off
	v_lshl_or_b32 v4, v3, 5, v12
	v_ashrrev_i32_e32 v3, 31, v2
	s_mov_b32 m0, s5
	s_ashr_i32 s5, s4, 31
	v_lshlrev_b64 v[24:25], 11, v[2:3]
	s_lshl_b64 s[96:97], s[4:5], 11
	v_lshl_add_u64 v[2:3], s[16:17], 0, v[24:25]
	s_add_u32 s16, s20, s96
	v_ashrrev_i32_e32 v5, 31, v4
	s_addc_u32 s17, s21, s97
	v_lshlrev_b64 v[26:27], 1, v[4:5]
	v_lshl_add_u64 v[4:5], s[16:17], 0, v[20:21]
	v_lshl_add_u64 v[6:7], s[16:17], 0, v[24:25]
	s_or_b32 s16, s92, 0x80
	s_ashr_i32 s17, s16, 31
	s_lshl_b64 s[16:17], s[16:17], 11
	s_add_u32 s16, s12, s16
	s_addc_u32 s17, s13, s17
	v_lshl_add_u64 v[8:9], s[16:17], 0, v[20:21]
	v_lshl_add_u64 v[10:11], s[16:17], 0, v[24:25]
	s_or_b32 s16, s4, 0x80
	v_lshl_add_u64 v[2:3], v[2:3], 0, v[26:27]
	v_readfirstlane_b32 s5, v145
	s_ashr_i32 s17, s16, 31
	global_load_lds_dwordx4 v[2:3], off
	v_lshl_add_u64 v[4:5], v[4:5], 0, v[22:23]
	s_mov_b32 m0, s5
	v_readfirstlane_b32 s5, v147
	v_add_u32_e32 v154, 0x14000, v145
	s_lshl_b64 s[16:17], s[16:17], 11
	global_load_lds_dwordx4 v[4:5], off
	v_lshl_add_u64 v[6:7], v[6:7], 0, v[26:27]
	s_mov_b32 m0, s5
	v_readfirstlane_b32 s5, v154
	v_add_u32_e32 v155, 0x16000, v145
	s_add_u32 s16, s20, s16
	global_load_lds_dwordx4 v[6:7], off
	v_lshl_add_u64 v[8:9], v[8:9], 0, v[22:23]
	s_mov_b32 m0, s5
	v_readfirstlane_b32 s5, v155
	s_addc_u32 s17, s21, s17
	v_add_u32_e32 v156, 0x4000, v145
	global_load_lds_dwordx4 v[8:9], off
	v_lshl_add_u64 v[10:11], v[10:11], 0, v[26:27]
	s_mov_b32 m0, s5
	v_lshl_add_u64 v[20:21], s[16:17], 0, v[20:21]
	v_readfirstlane_b32 s5, v156
	v_add_u32_e32 v157, 0x6000, v145
	global_load_lds_dwordx4 v[10:11], off
	v_lshl_add_u64 v[130:131], v[20:21], 0, v[22:23]
	s_mov_b32 m0, s5
	v_lshl_add_u64 v[20:21], s[16:17], 0, v[24:25]
	v_readfirstlane_b32 s5, v157
	global_load_lds_dwordx4 v[130:131], off
	v_lshl_add_u64 v[132:133], v[20:21], 0, v[26:27]
	s_mov_b32 m0, s5
	v_ashrrev_i32_e32 v20, 8, v128
	global_load_lds_dwordx4 v[132:133], off
	v_cmp_eq_u32_e32 vcc, 1, v20
	s_and_saveexec_b64 s[16:17], vcc
	s_cbranch_execz .LBB0_375
	s_barrier

; DEVI float frsq_(float x) { return __builtin_amdgcn_rsqf(x); }
; #define STAGE(P,BASE,br,kt) do{ long _g=(long)(br)*K+(long)(kt)*BK; \
;     _Pragma("unroll") for(int _i=0;_i<2;++_i){ int _b=tid*16+_i*8192; int _r,_c; stage_rc<2>(_b,_r,_c); \
;       __builtin_amdgcn_global_load_lds((const unsigned*)(BASE+_g+(long)_r*K+_c), \
;         (__attribute__((address_space(3))) unsigned*)((char*)(P)+_b),16,0,0);} }while(0)
; #define BAR __builtin_amdgcn_s_barrier()
; template <int EPI, bool SWAP>
; DEVI void gemm_tile(const Params& p, char* shm_, const u16* __restrict__ A, const u16* __restrict__ Bt, int K, int brow, int bcol,
;                     float* rst, const EpiArgs& ea) {
;     ...
;   if (ea.ss != nullptr && tid < 256) rst[tid] = frsq_(ea.ss[brow + tid] * (1.f / DM) + EPS);
;   u16* shm = (u16*)shm_;
;     ...
;   const int wid=tid>>6,lane=tid&63,wr=wid>>2,wc=wid&3,fr=lane&15,fq=lane>>4;
;   f32x4 acc[8][4];
; #pragma unroll
;   for (int m = 0; m < 8; ++m)
; #pragma unroll
;     for (int n = 0; n < 4; ++n) acc[m][n] = f32x4{0.f, 0.f, 0.f, 0.f};
;   bf16x8 At[4][2],B0[2][2],B1[2][2];
;   const int nt=K/BK;
;   STAGE(SB(0,0),Bt,bcol,0); STAGE(SA(0,0),A,brow,0);
;   STAGE(SB(0,1),Bt,bcol+HALF,0); STAGE(SA(0,1),A,brow+HALF,0);
;   if(wr==1)BAR;
; template <int EPI>
; DEVI void gemm_phase(const Params& p, char* shm, const u16* __restrict__ A, const u16* __restrict__ Bt, int N, int K, const EpiArgs& ea) {
;     ...
;   for (int t = blockIdx.x; t < nwg; t += gridDim.x) {
;     float* rst = rsS + par * 256; par ^= 1;
;     int wgid = t;
;     { int q = nwg / NXCD, r = nwg % NXCD, xcd = wgid % NXCD, off = wgid / NXCD;
;       wgid = (xcd < r ? xcd * (q + 1) : r * (q + 1) + (xcd - r) * q) + off; }
;     int nig = WGM * nN, gid = wgid / nig, fm = gid * WGM, gsz = min(nM - fm, WGM);
;     int pm = fm + ((wgid % nig) % gsz), pn = (wgid % nig) / gsz, brow = pm * BM, bcol = pn * BM;
;     if constexpr (EPI == EPI_HG_IN) gemm_tile<EPI, false>(p, shm, A, Bt, K, brow, bcol, rst, ea);
;     else if constexpr (EPI == EPI_FOX_IN) {
;       if (tile_swap<EPI>(bcol)) gemm_tile<EPI, true>(p, shm, A, Bt, K, brow, bcol, rst, ea);
;       else gemm_tile<EPI, false>(p, shm, A, Bt, K, brow, bcol, rst, ea);
;     } else gemm_tile<EPI, true>(p, shm, A, Bt, K, brow, bcol, rst, ea);
.LBB0_415:
	s_ashr_i32 s16, s79, 31
	s_lshr_b32 s16, s16, 29
	s_add_i32 s16, s79, s16
	s_lshl_b32 s80, s40, 10
	s_ashr_i32 s17, s16, 3
	s_and_b32 s16, s16, -8
	s_add_i32 s80, s80, 0x20000
	s_sub_i32 s16, s79, s16
	s_cmp_lt_i32 s16, 0
	s_cselect_b32 s52, s41, 0x160
	s_mul_i32 s16, s52, s16
	s_add_i32 s16, s16, s17
	s_mul_hi_i32 s17, s16, 0x2e8ba2e9
	s_lshr_b32 s52, s17, 31
	s_ashr_i32 s17, s17, 5
	s_add_i32 s17, s17, s52
	s_mul_i32 s52, s17, 0xb0
	s_sub_i32 s52, s16, s52
	s_sext_i32_i16 s16, s52
	s_bfe_u32 s16, s16, 0x3001c
	s_add_i32 s16, s52, s16
	s_and_b32 s53, s16, 0xfff8
	s_sub_i32 s52, s52, s53
	s_sext_i32_i16 s52, s52
	s_lshl_b32 s17, s17, 11
	s_lshl_b32 s52, s52, 8
	v_mov_b32_e32 v141, v220
	s_add_i32 s52, s52, s17
	s_nop 0
	v_cmp_gt_i32_e32 vcc, s45, v141
	s_and_saveexec_b64 s[54:55], vcc
	s_cbranch_execz .LBB0_417
	v_add_u32_e32 v0, s52, v141
	v_ashrrev_i32_e32 v1, 31, v0
	v_lshl_add_u64 v[0:1], v[0:1], 2, s[10:11]
	global_load_dword v221, v[0:1], off
	v_lshl_add_u32 v223, v141, 2, s80
.LBB0_417:
	s_or_b64 exec, exec, s[54:55]
	v_lshlrev_b32_e32 v144, 4, v141
	v_and_b32_e32 v0, 32, v141
	v_bitop3_b32 v0, v144, v0, 48 bitop3:0x6c
	v_lshrrev_b32_e32 v12, 1, v0
	v_ashrrev_i32_e32 v14, 6, v141
	v_lshrrev_b32_e32 v0, 31, v141
	v_add_u32_e32 v1, v14, v0
	v_ashrrev_i32_e32 v15, 1, v1
	v_and_b32_e32 v1, 0x7fffffe, v1
	v_sub_u32_e32 v1, v14, v1
	v_lshl_or_b32 v2, v1, 5, v12
	v_add_u32_e32 v146, 0x2000, v144
	s_sext_i32_i16 s16, s16
	v_ashrrev_i32_e32 v3, 31, v2
	v_ashrrev_i32_e32 v17, 10, v146
	s_lshr_b32 s16, s16, 3
	v_lshlrev_b64 v[22:23], 1, v[2:3]
	v_lshrrev_b32_e32 v2, 31, v17
	s_sext_i32_i16 s81, s16
	v_add_u32_e32 v3, v17, v2
	s_lshl_b32 s16, s81, 8
	v_ashrrev_i32_e32 v18, 1, v3
	s_ashr_i32 s17, s16, 31
	v_bfe_u32 v13, v141, 2, 4
	v_lshlrev_b32_e32 v16, 4, v15
	v_lshlrev_b32_e32 v19, 4, v18
	v_and_b32_e32 v3, 0x7fffffe, v3
	s_lshl_b64 s[54:55], s[16:17], 11
	v_or_b32_e32 v0, v16, v13
	v_or_b32_e32 v2, v19, v13
	v_sub_u32_e32 v3, v17, v3
	s_add_u32 s56, s4, s54
	v_ashrrev_i32_e32 v1, 31, v0
	v_lshl_or_b32 v4, v3, 5, v12
	v_ashrrev_i32_e32 v3, 31, v2
	s_addc_u32 s57, s5, s55
	v_lshlrev_b64 v[20:21], 11, v[0:1]
	v_lshlrev_b64 v[24:25], 11, v[2:3]
	s_ashr_i32 s53, s52, 31
	v_lshl_add_u64 v[0:1], s[56:57], 0, v[20:21]
	v_add_u32_e32 v145, 0x10000, v144
	v_lshl_add_u64 v[2:3], s[56:57], 0, v[24:25]
	s_lshl_b64 s[56:57], s[52:53], 11
	v_readfirstlane_b32 s17, v145
	v_ashrrev_i32_e32 v5, 31, v4
	v_add_u32_e32 v151, 0x12000, v144
	s_add_u32 s82, s38, s56
	v_lshl_add_u64 v[0:1], v[0:1], 0, v[22:23]
	s_mov_b32 m0, s17
	v_lshlrev_b64 v[26:27], 1, v[4:5]
	v_readfirstlane_b32 s17, v151
	s_addc_u32 s83, s39, s57
	global_load_lds_dwordx4 v[0:1], off
	v_lshl_add_u64 v[2:3], v[2:3], 0, v[26:27]
	s_mov_b32 m0, s17
	v_lshl_add_u64 v[4:5], s[82:83], 0, v[20:21]
	v_readfirstlane_b32 s17, v144
	global_load_lds_dwordx4 v[2:3], off
	v_lshl_add_u64 v[4:5], v[4:5], 0, v[22:23]
	s_mov_b32 m0, s17
	v_readfirstlane_b32 s17, v146
	s_bitset1_b32 s16, 7
	global_load_lds_dwordx4 v[4:5], off
	s_mov_b32 m0, s17
	s_ashr_i32 s17, s16, 31
	s_lshl_b64 s[16:17], s[16:17], 11
	s_add_u32 s16, s4, s16
	v_lshl_add_u64 v[6:7], s[82:83], 0, v[24:25]
	s_addc_u32 s17, s5, s17
	v_add_u32_e32 v153, 0x14000, v144
	v_lshl_add_u64 v[6:7], v[6:7], 0, v[26:27]
	v_lshl_add_u64 v[8:9], s[16:17], 0, v[20:21]
	v_readfirstlane_b32 s53, v153
	v_add_u32_e32 v154, 0x16000, v144
	global_load_lds_dwordx4 v[6:7], off
	v_lshl_add_u64 v[8:9], v[8:9], 0, v[22:23]
	s_mov_b32 m0, s53
	v_lshl_add_u64 v[10:11], s[16:17], 0, v[24:25]
	v_readfirstlane_b32 s16, v154
	global_load_lds_dwordx4 v[8:9], off
	s_mov_b32 m0, s16
	s_or_b32 s16, s52, 0x80
	s_ashr_i32 s17, s16, 31
	s_lshl_b64 s[16:17], s[16:17], 11
	s_add_u32 s16, s38, s16
	s_addc_u32 s17, s39, s17
	v_add_u32_e32 v156, 0x4000, v144
	v_lshl_add_u64 v[10:11], v[10:11], 0, v[26:27]
	v_lshl_add_u64 v[20:21], s[16:17], 0, v[20:21]
	v_readfirstlane_b32 s53, v156
	v_add_u32_e32 v157, 0x6000, v144
	global_load_lds_dwordx4 v[10:11], off
	v_lshl_add_u64 v[128:129], v[20:21], 0, v[22:23]
	s_mov_b32 m0, s53
	v_lshl_add_u64 v[20:21], s[16:17], 0, v[24:25]
	v_readfirstlane_b32 s16, v157
	global_load_lds_dwordx4 v[128:129], off
	v_lshl_add_u64 v[130:131], v[20:21], 0, v[26:27]
	s_mov_b32 m0, s16
	v_ashrrev_i32_e32 v20, 8, v141
	global_load_lds_dwordx4 v[130:131], off
	v_cmp_eq_u32_e32 vcc, 1, v20
	s_and_saveexec_b64 s[16:17], vcc
	s_cbranch_execz .LBB0_419
	s_barrier
; #define STAGE(P,BASE,br,kt) do{ long _g=(long)(br)*K+(long)(kt)*BK; \
;     _Pragma("unroll") for(int _i=0;_i<2;++_i){ int _b=tid*16+_i*8192; int _r,_c; stage_rc<2>(_b,_r,_c); \
;       __builtin_amdgcn_global_load_lds((const unsigned*)(BASE+_g+(long)_r*K+_c), \
;         (__attribute__((address_space(3))) unsigned*)((char*)(P)+_b),16,0,0);} }while(0)
; #define WAIT_VN(n) asm volatile("s_waitcnt vmcnt(" #n ")":::"memory")
; #define BAR __builtin_amdgcn_s_barrier()
; template <int EPI, bool SWAP>
; DEVI void gemm_tile(const Params& p, char* shm_, const u16* __restrict__ A, const u16* __restrict__ Bt, int K, int brow, int bcol,
;                     float* rst, const EpiArgs& ea) {
;     ...
;   f32x4 acc[8][4];
; #pragma unroll
;   for (int m = 0; m < 8; ++m)
; #pragma unroll
;     for (int n = 0; n < 4; ++n) acc[m][n] = f32x4{0.f, 0.f, 0.f, 0.f};
;   bf16x8 At[4][2],B0[2][2],B1[2][2];
;   const int nt=K/BK;
;   STAGE(SB(0,0),Bt,bcol,0); STAGE(SA(0,0),A,brow,0);
;   STAGE(SB(0,1),Bt,bcol+HALF,0); STAGE(SA(0,1),A,brow+HALF,0);
;   if(wr==1)BAR;
;   WAIT_VN(4); BAR;
;   STAGE(SB(1,0),Bt,bcol,1); STAGE(SA(1,0),A,brow,1); STAGE(SB(1,1),Bt,bcol+HALF,1);
;   WAIT_VN(6); BAR;
.LBB0_419:
	s_or_b64 exec, exec, s[16:17]
	v_add_u32_e32 v158, 0x18000, v144
	v_add_u32_e32 v159, 0x1a000, v144
	v_readfirstlane_b32 s16, v158
	v_lshl_add_u64 v[0:1], v[0:1], 0, s[12:13]
	s_mov_b32 m0, s16
	v_readfirstlane_b32 s16, v159
	v_add_u32_e32 v160, 0x8000, v144
	s_waitcnt vmcnt(4)
	s_barrier
	global_load_lds_dwordx4 v[0:1], off
	v_lshl_add_u64 v[0:1], v[2:3], 0, s[12:13]
	s_mov_b32 m0, s16
	v_readfirstlane_b32 s16, v160
	v_add_u32_e32 v161, 0xa000, v144
	global_load_lds_dwordx4 v[0:1], off
	v_lshl_add_u64 v[0:1], v[4:5], 0, s[12:13]
	s_mov_b32 m0, s16
	v_readfirstlane_b32 s16, v161
	v_add_u32_e32 v162, 0x1c000, v144
	global_load_lds_dwordx4 v[0:1], off
	v_lshl_add_u64 v[0:1], v[6:7], 0, s[12:13]
	s_mov_b32 m0, s16
	v_readfirstlane_b32 s16, v162
	v_add_u32_e32 v163, 0x1e000, v144
	global_load_lds_dwordx4 v[0:1], off
	v_lshl_add_u64 v[0:1], v[8:9], 0, s[12:13]
	s_mov_b32 m0, s16
	v_readfirstlane_b32 s16, v163
	global_load_lds_dwordx4 v[0:1], off
	v_lshl_add_u64 v[0:1], v[10:11], 0, s[12:13]
	s_mov_b32 m0, s16
	v_and_b32_e32 v21, 15, v141
	global_load_lds_dwordx4 v[0:1], off
	v_lshlrev_b32_e32 v0, 6, v141
	v_lshlrev_b32_e32 v3, 2, v141
	v_and_b32_e32 v22, 48, v141
	v_and_b32_e32 v10, 0x3000, v0
	v_lshlrev_b32_e32 v1, 6, v21
	v_and_b32_e32 v3, 32, v3
	v_and_b32_e32 v0, 0x3c0, v0
	v_or_b32_e32 v2, v1, v22
	v_bitop3_b32 v11, v1, v3, v22 bitop3:0x36
	v_bitop3_b32 v22, v0, v3, v22 bitop3:0x36
	v_add_u32_e32 v0, v16, v13
	v_lshl_or_b32 v4, v14, 5, v12
	v_lshlrev_b32_e32 v5, 6, v15
	v_ashrrev_i32_e32 v1, 31, v0
	v_sub_u32_e32 v4, v4, v5
	v_lshlrev_b64 v[0:1], 11, v[0:1]
	v_ashrrev_i32_e32 v5, 31, v4
	v_bitop3_b32 v21, v2, s68, v3 bitop3:0xde
	v_bitop3_b32 v23, v2, s69, v3 bitop3:0xde
	v_bitop3_b32 v24, v2, s70, v3 bitop3:0xde
	v_bitop3_b32 v25, v2, s71, v3 bitop3:0xde
	v_lshl_add_u64 v[2:3], s[54:55], 0, v[0:1]
	v_lshlrev_b64 v[4:5], 1, v[4:5]
	v_lshl_add_u64 v[132:133], v[2:3], 0, v[4:5]
	v_add_u32_e32 v2, v19, v13
	v_lshl_or_b32 v8, v17, 5, v12
	v_lshlrev_b32_e32 v9, 6, v18
	v_ashrrev_i32_e32 v3, 31, v2
	v_sub_u32_e32 v8, v8, v9
	v_lshlrev_b64 v[2:3], 11, v[2:3]
	v_ashrrev_i32_e32 v9, 31, v8
	v_lshl_add_u64 v[0:1], s[56:57], 0, v[0:1]
	s_waitcnt vmcnt(6)
	v_lshlrev_b32_e32 v143, 6, v20
	v_lshlrev_b32_e32 v20, 13, v20
	v_lshlrev_b64 v[8:9], 1, v[8:9]
	v_lshl_add_u64 v[136:137], v[0:1], 0, v[4:5]
	v_lshl_add_u64 v[0:1], s[56:57], 0, v[2:3]
	v_or_b32_e32 v26, 0x800, v20
	v_or_b32_e32 v27, 0x1000, v20
	v_or_b32_e32 v28, 0x1800, v20
	v_lshl_add_u64 v[6:7], s[54:55], 0, v[2:3]
	v_lshl_add_u64 v[138:139], v[0:1], 0, v[8:9]
	v_mov_b32_e32 v0, 0
	v_lshrrev_b32_e32 v142, 6, v141
	v_lshl_add_u64 v[134:135], v[6:7], 0, v[8:9]
	s_mov_b32 s16, -2
	v_add_u32_e32 v167, v21, v10
	v_add_u32_e32 v150, v11, v20
	v_add_u32_e32 v149, v22, v26
	v_add_u32_e32 v148, v22, v27
	v_add_u32_e32 v147, v22, v28
	v_add_u32_e32 v166, 0xc000, v144
	v_add_u32_e32 v165, 0xe000, v144
	v_add_u32_e32 v164, v23, v10
	v_add_u32_e32 v155, v24, v10
	v_add_u32_e32 v152, v25, v10
	v_mov_b32_e32 v1, v0
	v_mov_b32_e32 v2, v0
	v_mov_b32_e32 v3, v0
	v_mov_b32_e32 v4, v0
	v_mov_b32_e32 v5, v0
	v_mov_b32_e32 v6, v0
	v_mov_b32_e32 v7, v0
	v_mov_b32_e32 v12, v0
	v_mov_b32_e32 v13, v0
	v_mov_b32_e32 v14, v0
	v_mov_b32_e32 v15, v0
	v_mov_b32_e32 v20, v0
	v_mov_b32_e32 v21, v0
	v_mov_b32_e32 v22, v0
	v_mov_b32_e32 v23, v0
	v_mov_b32_e32 v8, v0
	v_mov_b32_e32 v9, v0
	v_mov_b32_e32 v10, v0
	v_mov_b32_e32 v11, v0
	v_mov_b32_e32 v16, v0
	v_mov_b32_e32 v17, v0
	v_mov_b32_e32 v18, v0
	v_mov_b32_e32 v19, v0
	v_mov_b32_e32 v28, v0
	v_mov_b32_e32 v29, v0
	v_mov_b32_e32 v30, v0
	v_mov_b32_e32 v31, v0
	v_mov_b32_e32 v36, v0
	v_mov_b32_e32 v37, v0
	v_mov_b32_e32 v38, v0
	v_mov_b32_e32 v39, v0
	v_mov_b32_e32 v24, v0
	v_mov_b32_e32 v25, v0
	v_mov_b32_e32 v26, v0
	v_mov_b32_e32 v27, v0
	v_mov_b32_e32 v32, v0
	v_mov_b32_e32 v33, v0
	v_mov_b32_e32 v34, v0
	v_mov_b32_e32 v35, v0
	v_mov_b32_e32 v44, v0
	v_mov_b32_e32 v45, v0
	v_mov_b32_e32 v46, v0
	v_mov_b32_e32 v47, v0
	v_mov_b32_e32 v52, v0
	v_mov_b32_e32 v53, v0
	v_mov_b32_e32 v54, v0
	v_mov_b32_e32 v55, v0
	v_mov_b32_e32 v40, v0
	v_mov_b32_e32 v41, v0
	v_mov_b32_e32 v42, v0
	v_mov_b32_e32 v43, v0
	v_mov_b32_e32 v48, v0
	v_mov_b32_e32 v49, v0
	v_mov_b32_e32 v50, v0
	v_mov_b32_e32 v51, v0
	v_mov_b32_e32 v56, v0
	v_mov_b32_e32 v57, v0
	v_mov_b32_e32 v58, v0
	v_mov_b32_e32 v59, v0
	v_mov_b32_e32 v60, v0
	v_mov_b32_e32 v61, v0
	v_mov_b32_e32 v62, v0
	v_mov_b32_e32 v63, v0
	v_mov_b32_e32 v64, v0
	v_mov_b32_e32 v65, v0
	v_mov_b32_e32 v66, v0
	v_mov_b32_e32 v67, v0
	v_mov_b32_e32 v68, v0
	v_mov_b32_e32 v69, v0
	v_mov_b32_e32 v70, v0
	v_mov_b32_e32 v71, v0
	v_mov_b32_e32 v80, v0
	v_mov_b32_e32 v81, v0
	v_mov_b32_e32 v82, v0
	v_mov_b32_e32 v83, v0
	v_mov_b32_e32 v88, v0
	v_mov_b32_e32 v89, v0
	v_mov_b32_e32 v90, v0
	v_mov_b32_e32 v91, v0
	v_mov_b32_e32 v72, v0
	v_mov_b32_e32 v73, v0
	v_mov_b32_e32 v74, v0
	v_mov_b32_e32 v75, v0
	v_mov_b32_e32 v76, v0
	v_mov_b32_e32 v77, v0
	v_mov_b32_e32 v78, v0
	v_mov_b32_e32 v79, v0
	v_mov_b32_e32 v96, v0
	v_mov_b32_e32 v97, v0
	v_mov_b32_e32 v98, v0
	v_mov_b32_e32 v99, v0
	v_mov_b32_e32 v104, v0
	v_mov_b32_e32 v105, v0
	v_mov_b32_e32 v106, v0
	v_mov_b32_e32 v107, v0
	v_mov_b32_e32 v84, v0
	v_mov_b32_e32 v85, v0
	v_mov_b32_e32 v86, v0
	v_mov_b32_e32 v87, v0
	v_mov_b32_e32 v92, v0
	v_mov_b32_e32 v93, v0
	v_mov_b32_e32 v94, v0
	v_mov_b32_e32 v95, v0
	v_mov_b32_e32 v112, v0
	v_mov_b32_e32 v113, v0
	v_mov_b32_e32 v114, v0
	v_mov_b32_e32 v115, v0
	v_mov_b32_e32 v116, v0
	v_mov_b32_e32 v117, v0
	v_mov_b32_e32 v118, v0
	v_mov_b32_e32 v119, v0
	v_mov_b32_e32 v100, v0
	v_mov_b32_e32 v101, v0
	v_mov_b32_e32 v102, v0
	v_mov_b32_e32 v103, v0
	v_mov_b32_e32 v108, v0
	v_mov_b32_e32 v109, v0
	v_mov_b32_e32 v110, v0
	v_mov_b32_e32 v111, v0
	v_mov_b32_e32 v120, v0
	v_mov_b32_e32 v121, v0
	v_mov_b32_e32 v122, v0
	v_mov_b32_e32 v123, v0
	v_mov_b32_e32 v124, v0
	v_mov_b32_e32 v125, v0
	v_mov_b32_e32 v126, v0
	v_mov_b32_e32 v127, v0
	s_movk_i32 s98, 0x100
	v_cmp_gt_u32_e64 s[100:101], s98, v220
	s_and_saveexec_b64 s[98:99], s[100:101]
	v_mul_f32_e32 v221, 0x3a800000, v221
	v_add_f32_e32 v221, 0x358637bd, v221
	v_rsq_f32_e32 v221, v221
	ds_write_b32 v223, v221
	s_or_b64 exec, exec, s[98:99]
	s_barrier

; DEVI float frsq_(float x) { return __builtin_amdgcn_rsqf(x); }
; template <int EPI, bool SWAP>
; DEVI void gemm_tile(const Params& p, char* shm_, const u16* __restrict__ A, const u16* __restrict__ Bt, int K, int brow, int bcol,
;                     float* rst, const EpiArgs& ea) {
;     ...
;   if (ea.ss != nullptr && tid < 256) rst[tid] = frsq_(ea.ss[brow + tid] * (1.f / DM) + EPS);
; template <int EPI>
; DEVI void gemm_phase(const Params& p, char* shm, const u16* __restrict__ A, const u16* __restrict__ Bt, int N, int K, const EpiArgs& ea) {
;     ...
;   for (int t = blockIdx.x; t < nwg; t += gridDim.x) {
;     float* rst = rsS + par * 256; par ^= 1;
;     int wgid = t;
;     { int q = nwg / NXCD, r = nwg % NXCD, xcd = wgid % NXCD, off = wgid / NXCD;
;       wgid = (xcd < r ? xcd * (q + 1) : r * (q + 1) + (xcd - r) * q) + off; }
;     int nig = WGM * nN, gid = wgid / nig, fm = gid * WGM, gsz = min(nM - fm, WGM);
;     int pm = fm + ((wgid % nig) % gsz), pn = (wgid % nig) / gsz, brow = pm * BM, bcol = pn * BM;
;     if constexpr (EPI == EPI_HG_IN) gemm_tile<EPI, false>(p, shm, A, Bt, K, brow, bcol, rst, ea);
;     else if constexpr (EPI == EPI_FOX_IN) {
;       if (tile_swap<EPI>(bcol)) gemm_tile<EPI, true>(p, shm, A, Bt, K, brow, bcol, rst, ea);
;       else gemm_tile<EPI, false>(p, shm, A, Bt, K, brow, bcol, rst, ea);
;     } else gemm_tile<EPI, true>(p, shm, A, Bt, K, brow, bcol, rst, ea);
.LBB0_491:
	s_ashr_i32 s8, s10, 3
	s_add_i32 s8, s11, s8
	s_ashr_i32 s9, s8, 31
	s_lshr_b32 s9, s9, 25
	s_add_i32 s10, s8, s9
	s_and_b32 s9, s10, 0xff80
	s_sub_i32 s8, s8, s9
	s_bfe_i32 s9, s8, 0x80000
	s_bfe_u32 s9, s9, 0x3000c
	s_add_i32 s9, s8, s9
	s_and_b32 s11, s9, 0xf8
	s_sub_i32 s8, s8, s11
	s_sext_i32_i8 s8, s8
	s_lshl_b32 s10, s10, 4
	s_lshl_b32 s18, s40, 10
	s_and_b32 s10, s10, 0xfffff800
	s_lshl_b32 s8, s8, 8
	v_mov_b32_e32 v133, v220
	s_add_i32 s18, s18, 0x20000
	s_add_i32 s8, s8, s10
	s_nop 0
	v_cmp_gt_i32_e32 vcc, s41, v133
	s_and_saveexec_b64 s[10:11], vcc
	s_cbranch_execz .LBB0_493
	v_add_u32_e32 v0, s8, v133
	v_ashrrev_i32_e32 v1, 31, v0
	v_lshl_add_u64 v[0:1], v[0:1], 2, s[22:23]
	global_load_dword v221, v[0:1], off
	v_lshl_add_u32 v223, v133, 2, s18

; #define STAGE(P,BASE,br,kt) do{ long _g=(long)(br)*K+(long)(kt)*BK; \
;     _Pragma("unroll") for(int _i=0;_i<2;++_i){ int _b=tid*16+_i*8192; int _r,_c; stage_rc<2>(_b,_r,_c); \
;       __builtin_amdgcn_global_load_lds((const unsigned*)(BASE+_g+(long)_r*K+_c), \
;         (__attribute__((address_space(3))) unsigned*)((char*)(P)+_b),16,0,0);} }while(0)
; #define WAIT_VN(n) asm volatile("s_waitcnt vmcnt(" #n ")":::"memory")
; #define BAR __builtin_amdgcn_s_barrier()
; template <int EPI, bool SWAP>
; DEVI void gemm_tile(const Params& p, char* shm_, const u16* __restrict__ A, const u16* __restrict__ Bt, int K, int brow, int bcol,
;                     float* rst, const EpiArgs& ea) {
;     ...
;   f32x4 acc[8][4];
; #pragma unroll
;   for (int m = 0; m < 8; ++m)
; #pragma unroll
;     for (int n = 0; n < 4; ++n) acc[m][n] = f32x4{0.f, 0.f, 0.f, 0.f};
;   bf16x8 At[4][2],B0[2][2],B1[2][2];
;   const int nt=K/BK;
;   STAGE(SB(0,0),Bt,bcol,0); STAGE(SA(0,0),A,brow,0);
;   STAGE(SB(0,1),Bt,bcol+HALF,0); STAGE(SA(0,1),A,brow+HALF,0);
;   if(wr==1)BAR;
;   WAIT_VN(4); BAR;
;   STAGE(SB(1,0),Bt,bcol,1); STAGE(SA(1,0),A,brow,1); STAGE(SB(1,1),Bt,bcol+HALF,1);
;   WAIT_VN(6); BAR;
.LBB0_495:
	s_or_b64 exec, exec, s[16:17]
	v_add_u32_e32 v158, 0x18000, v144
	v_add_u32_e32 v159, 0x1a000, v144
	v_readfirstlane_b32 s9, v158
	v_lshl_add_u64 v[0:1], v[0:1], 0, s[28:29]
	s_mov_b32 m0, s9
	v_readfirstlane_b32 s9, v159
	v_add_u32_e32 v160, 0x8000, v144
	s_waitcnt vmcnt(4)
	s_barrier
	global_load_lds_dwordx4 v[0:1], off
	v_lshl_add_u64 v[0:1], v[2:3], 0, s[28:29]
	s_mov_b32 m0, s9
	v_readfirstlane_b32 s9, v160
	v_add_u32_e32 v161, 0xa000, v144
	global_load_lds_dwordx4 v[0:1], off
	v_lshl_add_u64 v[0:1], v[4:5], 0, s[28:29]
	s_mov_b32 m0, s9
	v_readfirstlane_b32 s9, v161
	v_add_u32_e32 v162, 0x1c000, v144
	global_load_lds_dwordx4 v[0:1], off
	v_lshl_add_u64 v[0:1], v[6:7], 0, s[28:29]
	s_mov_b32 m0, s9
	v_readfirstlane_b32 s9, v162
	v_add_u32_e32 v163, 0x1e000, v144
	global_load_lds_dwordx4 v[0:1], off
	v_lshl_add_u64 v[0:1], v[8:9], 0, s[28:29]
	s_mov_b32 m0, s9
	v_readfirstlane_b32 s9, v163
	global_load_lds_dwordx4 v[0:1], off
	v_lshl_add_u64 v[0:1], v[10:11], 0, s[28:29]
	s_mov_b32 m0, s9
	v_and_b32_e32 v21, 15, v133
	global_load_lds_dwordx4 v[0:1], off
	v_lshlrev_b32_e32 v0, 6, v133
	v_lshlrev_b32_e32 v3, 2, v133
	v_and_b32_e32 v22, 48, v133
	v_and_b32_e32 v10, 0x3000, v0
	v_lshlrev_b32_e32 v1, 6, v21
	v_and_b32_e32 v3, 32, v3
	v_and_b32_e32 v0, 0x3c0, v0
	v_or_b32_e32 v2, v1, v22
	v_bitop3_b32 v11, v1, v3, v22 bitop3:0x36
	v_bitop3_b32 v22, v0, v3, v22 bitop3:0x36
	v_add_u32_e32 v0, v16, v13
	v_lshl_or_b32 v4, v14, 5, v12
	v_lshlrev_b32_e32 v5, 6, v15
	v_ashrrev_i32_e32 v1, 31, v0
	v_sub_u32_e32 v4, v4, v5
	v_lshlrev_b64 v[0:1], 11, v[0:1]
	v_ashrrev_i32_e32 v5, 31, v4
	v_bitop3_b32 v21, v2, s45, v3 bitop3:0xde
	v_bitop3_b32 v23, v2, s80, v3 bitop3:0xde
	v_bitop3_b32 v24, v2, s81, v3 bitop3:0xde
	v_bitop3_b32 v25, v2, s82, v3 bitop3:0xde
	v_lshl_add_u64 v[2:3], s[10:11], 0, v[0:1]
	v_lshlrev_b64 v[4:5], 1, v[4:5]
	v_lshl_add_u64 v[134:135], v[2:3], 0, v[4:5]
	v_add_u32_e32 v2, v19, v13
	v_lshl_or_b32 v8, v17, 5, v12
	v_lshlrev_b32_e32 v9, 6, v18
	v_ashrrev_i32_e32 v3, 31, v2
	v_sub_u32_e32 v8, v8, v9
	v_lshlrev_b64 v[2:3], 11, v[2:3]
	v_ashrrev_i32_e32 v9, 31, v8
	v_lshl_add_u64 v[0:1], s[12:13], 0, v[0:1]
	s_waitcnt vmcnt(6)
	v_lshlrev_b32_e32 v143, 6, v20
	v_lshlrev_b32_e32 v20, 13, v20
	v_lshlrev_b64 v[8:9], 1, v[8:9]
	v_lshl_add_u64 v[138:139], v[0:1], 0, v[4:5]
	v_lshl_add_u64 v[0:1], s[12:13], 0, v[2:3]
	v_or_b32_e32 v26, 0x800, v20
	v_or_b32_e32 v27, 0x1000, v20
	v_or_b32_e32 v28, 0x1800, v20
	v_lshl_add_u64 v[6:7], s[10:11], 0, v[2:3]
	v_lshl_add_u64 v[140:141], v[0:1], 0, v[8:9]
	v_mov_b32_e32 v0, 0
	v_lshrrev_b32_e32 v142, 6, v133
	v_lshl_add_u64 v[136:137], v[6:7], 0, v[8:9]
	s_mov_b32 s9, -2
	v_add_u32_e32 v170, v21, v10
	v_add_u32_e32 v150, v11, v20
	v_add_u32_e32 v149, v22, v26
	v_add_u32_e32 v148, v22, v27
	v_add_u32_e32 v147, v22, v28
	v_add_u32_e32 v169, 0xc000, v144
	v_add_u32_e32 v165, 0xe000, v144
	v_add_u32_e32 v164, v23, v10
	v_add_u32_e32 v155, v24, v10
	v_add_u32_e32 v152, v25, v10
	v_mov_b32_e32 v1, v0
	v_mov_b32_e32 v2, v0
	v_mov_b32_e32 v3, v0
	v_mov_b32_e32 v4, v0
	v_mov_b32_e32 v5, v0
	v_mov_b32_e32 v6, v0
	v_mov_b32_e32 v7, v0
	v_mov_b32_e32 v12, v0
	v_mov_b32_e32 v13, v0
	v_mov_b32_e32 v14, v0
	v_mov_b32_e32 v15, v0
	v_mov_b32_e32 v20, v0
	v_mov_b32_e32 v21, v0
	v_mov_b32_e32 v22, v0
	v_mov_b32_e32 v23, v0
	v_mov_b32_e32 v8, v0
	v_mov_b32_e32 v9, v0
	v_mov_b32_e32 v10, v0
	v_mov_b32_e32 v11, v0
	v_mov_b32_e32 v16, v0
	v_mov_b32_e32 v17, v0
	v_mov_b32_e32 v18, v0
	v_mov_b32_e32 v19, v0
	v_mov_b32_e32 v28, v0
	v_mov_b32_e32 v29, v0
	v_mov_b32_e32 v30, v0
	v_mov_b32_e32 v31, v0
	v_mov_b32_e32 v36, v0
	v_mov_b32_e32 v37, v0
	v_mov_b32_e32 v38, v0
	v_mov_b32_e32 v39, v0
	v_mov_b32_e32 v24, v0
	v_mov_b32_e32 v25, v0
	v_mov_b32_e32 v26, v0
	v_mov_b32_e32 v27, v0
	v_mov_b32_e32 v32, v0
	v_mov_b32_e32 v33, v0
	v_mov_b32_e32 v34, v0
	v_mov_b32_e32 v35, v0
	v_mov_b32_e32 v44, v0
	v_mov_b32_e32 v45, v0
	v_mov_b32_e32 v46, v0
	v_mov_b32_e32 v47, v0
	v_mov_b32_e32 v52, v0
	v_mov_b32_e32 v53, v0
	v_mov_b32_e32 v54, v0
	v_mov_b32_e32 v55, v0
	v_mov_b32_e32 v40, v0
	v_mov_b32_e32 v41, v0
	v_mov_b32_e32 v42, v0
	v_mov_b32_e32 v43, v0
	v_mov_b32_e32 v48, v0
	v_mov_b32_e32 v49, v0
	v_mov_b32_e32 v50, v0
	v_mov_b32_e32 v51, v0
	v_mov_b32_e32 v56, v0
	v_mov_b32_e32 v57, v0
	v_mov_b32_e32 v58, v0
	v_mov_b32_e32 v59, v0
	v_mov_b32_e32 v60, v0
	v_mov_b32_e32 v61, v0
	v_mov_b32_e32 v62, v0
	v_mov_b32_e32 v63, v0
	v_mov_b32_e32 v64, v0
	v_mov_b32_e32 v65, v0
	v_mov_b32_e32 v66, v0
	v_mov_b32_e32 v67, v0
	v_mov_b32_e32 v68, v0
	v_mov_b32_e32 v69, v0
	v_mov_b32_e32 v70, v0
	v_mov_b32_e32 v71, v0
	v_mov_b32_e32 v80, v0
	v_mov_b32_e32 v81, v0
	v_mov_b32_e32 v82, v0
	v_mov_b32_e32 v83, v0
	v_mov_b32_e32 v88, v0
	v_mov_b32_e32 v89, v0
	v_mov_b32_e32 v90, v0
	v_mov_b32_e32 v91, v0
	v_mov_b32_e32 v72, v0
	v_mov_b32_e32 v73, v0
	v_mov_b32_e32 v74, v0
	v_mov_b32_e32 v75, v0
	v_mov_b32_e32 v76, v0
	v_mov_b32_e32 v77, v0
	v_mov_b32_e32 v78, v0
	v_mov_b32_e32 v79, v0
	v_mov_b32_e32 v96, v0
	v_mov_b32_e32 v97, v0
	v_mov_b32_e32 v98, v0
	v_mov_b32_e32 v99, v0
	v_mov_b32_e32 v104, v0
	v_mov_b32_e32 v105, v0
	v_mov_b32_e32 v106, v0
	v_mov_b32_e32 v107, v0
	v_mov_b32_e32 v84, v0
	v_mov_b32_e32 v85, v0
	v_mov_b32_e32 v86, v0
	v_mov_b32_e32 v87, v0
	v_mov_b32_e32 v92, v0
	v_mov_b32_e32 v93, v0
	v_mov_b32_e32 v94, v0
	v_mov_b32_e32 v95, v0
	v_mov_b32_e32 v112, v0
	v_mov_b32_e32 v113, v0
	v_mov_b32_e32 v114, v0
	v_mov_b32_e32 v115, v0
	v_mov_b32_e32 v116, v0
	v_mov_b32_e32 v117, v0
	v_mov_b32_e32 v118, v0
	v_mov_b32_e32 v119, v0
	v_mov_b32_e32 v100, v0
	v_mov_b32_e32 v101, v0
	v_mov_b32_e32 v102, v0
	v_mov_b32_e32 v103, v0
	v_mov_b32_e32 v108, v0
	v_mov_b32_e32 v109, v0
	v_mov_b32_e32 v110, v0
	v_mov_b32_e32 v111, v0
	v_mov_b32_e32 v120, v0
	v_mov_b32_e32 v121, v0
	v_mov_b32_e32 v122, v0
	v_mov_b32_e32 v123, v0
	v_mov_b32_e32 v124, v0
	v_mov_b32_e32 v125, v0
	v_mov_b32_e32 v126, v0
	v_mov_b32_e32 v127, v0
	s_movk_i32 s98, 0x100
	v_cmp_gt_u32_e64 s[100:101], s98, v220
	s_and_saveexec_b64 s[98:99], s[100:101]
	v_mul_f32_e32 v221, 0x3a800000, v221
	v_add_f32_e32 v221, 0x358637bd, v221
	v_rsq_f32_e32 v221, v221
	ds_write_b32 v223, v221
	s_or_b64 exec, exec, s[98:99]
	s_barrier

; DEVI float frsq_(float x) { return __builtin_amdgcn_rsqf(x); }
; template <int EPI, bool SWAP>
; DEVI void gemm_tile(const Params& p, char* shm_, const u16* __restrict__ A, const u16* __restrict__ Bt, int K, int brow, int bcol,
;                     float* rst, const EpiArgs& ea) {
;     ...
;   if (ea.ss != nullptr && tid < 256) rst[tid] = frsq_(ea.ss[brow + tid] * (1.f / DM) + EPS);
; template <int EPI>
; DEVI void gemm_phase(const Params& p, char* shm, const u16* __restrict__ A, const u16* __restrict__ Bt, int N, int K, const EpiArgs& ea) {
;     ...
;   for (int t = blockIdx.x; t < nwg; t += gridDim.x) {
;     float* rst = rsS + par * 256; par ^= 1;
;     int wgid = t;
;     { int q = nwg / NXCD, r = nwg % NXCD, xcd = wgid % NXCD, off = wgid / NXCD;
;       wgid = (xcd < r ? xcd * (q + 1) : r * (q + 1) + (xcd - r) * q) + off; }
;     int nig = WGM * nN, gid = wgid / nig, fm = gid * WGM, gsz = min(nM - fm, WGM);
;     int pm = fm + ((wgid % nig) % gsz), pn = (wgid % nig) / gsz, brow = pm * BM, bcol = pn * BM;
;     if constexpr (EPI == EPI_HG_IN) gemm_tile<EPI, false>(p, shm, A, Bt, K, brow, bcol, rst, ea);
;     else if constexpr (EPI == EPI_FOX_IN) {
;       if (tile_swap<EPI>(bcol)) gemm_tile<EPI, true>(p, shm, A, Bt, K, brow, bcol, rst, ea);
;       else gemm_tile<EPI, false>(p, shm, A, Bt, K, brow, bcol, rst, ea);
;     } else gemm_tile<EPI, true>(p, shm, A, Bt, K, brow, bcol, rst, ea);
.LBB0_619:
	s_ashr_i32 s36, s61, 31
	s_lshr_b32 s36, s36, 29
	s_add_i32 s36, s61, s36
	s_lshl_b32 s62, s45, 10
	s_ashr_i32 s37, s36, 3
	s_and_b32 s36, s36, -8
	s_add_i32 s62, s62, 0x20000
	s_sub_i32 s36, s61, s36
	s_cmp_lt_i32 s36, 0
	s_cselect_b32 s40, s54, 0x160
	s_mul_i32 s36, s40, s36
	s_add_i32 s36, s36, s37
	s_mul_hi_i32 s37, s36, 0x2e8ba2e9
	s_lshr_b32 s40, s37, 31
	s_ashr_i32 s37, s37, 5
	s_add_i32 s40, s37, s40
	s_mul_i32 s37, s40, 0xb0
	s_sub_i32 s36, s36, s37
	s_sext_i32_i16 s37, s36
	s_bfe_u32 s37, s37, 0x3001c
	s_add_i32 s37, s36, s37
	s_and_b32 s41, s37, 0xfff8
	s_sub_i32 s36, s36, s41
	s_sext_i32_i16 s36, s36
	s_lshl_b32 s40, s40, 11
	s_lshl_b32 s36, s36, 8
	v_mov_b32_e32 v141, v220
	s_add_i32 s36, s36, s40
	s_nop 0
	v_cmp_gt_i32_e32 vcc, s55, v141
	s_and_saveexec_b64 s[40:41], vcc
	s_cbranch_execz .LBB0_621
	v_add_u32_e32 v0, s36, v141
	v_ashrrev_i32_e32 v1, 31, v0
	v_lshl_add_u64 v[0:1], v[0:1], 2, s[10:11]
	global_load_dword v221, v[0:1], off
	v_lshl_add_u32 v223, v141, 2, s62

; #define STAGE(P,BASE,br,kt) do{ long _g=(long)(br)*K+(long)(kt)*BK; \
;     _Pragma("unroll") for(int _i=0;_i<2;++_i){ int _b=tid*16+_i*8192; int _r,_c; stage_rc<2>(_b,_r,_c); \
;       __builtin_amdgcn_global_load_lds((const unsigned*)(BASE+_g+(long)_r*K+_c), \
;         (__attribute__((address_space(3))) unsigned*)((char*)(P)+_b),16,0,0);} }while(0)
; #define WAIT_VN(n) asm volatile("s_waitcnt vmcnt(" #n ")":::"memory")
; #define BAR __builtin_amdgcn_s_barrier()
; template <int EPI, bool SWAP>
; DEVI void gemm_tile(const Params& p, char* shm_, const u16* __restrict__ A, const u16* __restrict__ Bt, int K, int brow, int bcol,
;                     float* rst, const EpiArgs& ea) {
;     ...
;   f32x4 acc[8][4];
; #pragma unroll
;   for (int m = 0; m < 8; ++m)
; #pragma unroll
;     for (int n = 0; n < 4; ++n) acc[m][n] = f32x4{0.f, 0.f, 0.f, 0.f};
;   bf16x8 At[4][2],B0[2][2],B1[2][2];
;   const int nt=K/BK;
;   STAGE(SB(0,0),Bt,bcol,0); STAGE(SA(0,0),A,brow,0);
;   STAGE(SB(0,1),Bt,bcol+HALF,0); STAGE(SA(0,1),A,brow+HALF,0);
;   if(wr==1)BAR;
;   WAIT_VN(4); BAR;
;   STAGE(SB(1,0),Bt,bcol,1); STAGE(SA(1,0),A,brow,1); STAGE(SB(1,1),Bt,bcol+HALF,1);
;   WAIT_VN(6); BAR;
.LBB0_623:
	s_or_b64 exec, exec, s[52:53]
	v_add_u32_e32 v158, 0x18000, v144
	v_add_u32_e32 v159, 0x1a000, v144
	v_readfirstlane_b32 s37, v158
	v_lshl_add_u64 v[0:1], v[0:1], 0, s[12:13]
	s_mov_b32 m0, s37
	v_readfirstlane_b32 s37, v159
	v_add_u32_e32 v160, 0x8000, v144
	s_waitcnt vmcnt(4)
	s_barrier
	global_load_lds_dwordx4 v[0:1], off
	v_lshl_add_u64 v[0:1], v[2:3], 0, s[12:13]
	s_mov_b32 m0, s37
	v_readfirstlane_b32 s37, v160
	v_add_u32_e32 v161, 0xa000, v144
	global_load_lds_dwordx4 v[0:1], off
	v_lshl_add_u64 v[0:1], v[4:5], 0, s[12:13]
	s_mov_b32 m0, s37
	v_readfirstlane_b32 s37, v161
	v_add_u32_e32 v162, 0x1c000, v144
	global_load_lds_dwordx4 v[0:1], off
	v_lshl_add_u64 v[0:1], v[6:7], 0, s[12:13]
	s_mov_b32 m0, s37
	v_readfirstlane_b32 s37, v162
	v_add_u32_e32 v163, 0x1e000, v144
	global_load_lds_dwordx4 v[0:1], off
	v_lshl_add_u64 v[0:1], v[8:9], 0, s[12:13]
	s_mov_b32 m0, s37
	v_readfirstlane_b32 s37, v163
	global_load_lds_dwordx4 v[0:1], off
	v_lshl_add_u64 v[0:1], v[10:11], 0, s[12:13]
	s_mov_b32 m0, s37
	v_and_b32_e32 v21, 15, v141
	global_load_lds_dwordx4 v[0:1], off
	v_lshlrev_b32_e32 v0, 6, v141
	v_lshlrev_b32_e32 v3, 2, v141
	v_and_b32_e32 v22, 48, v141
	v_and_b32_e32 v10, 0x3000, v0
	v_lshlrev_b32_e32 v1, 6, v21
	v_and_b32_e32 v3, 32, v3
	v_and_b32_e32 v0, 0x3c0, v0
	v_or_b32_e32 v2, v1, v22
	v_bitop3_b32 v11, v1, v3, v22 bitop3:0x36
	v_bitop3_b32 v22, v0, v3, v22 bitop3:0x36
	v_add_u32_e32 v0, v16, v13
	v_lshl_or_b32 v4, v14, 5, v12
	v_lshlrev_b32_e32 v5, 6, v15
	v_ashrrev_i32_e32 v1, 31, v0
	v_sub_u32_e32 v4, v4, v5
	v_lshlrev_b64 v[0:1], 11, v[0:1]
	v_ashrrev_i32_e32 v5, 31, v4
	v_bitop3_b32 v21, v2, s56, v3 bitop3:0xde
	v_bitop3_b32 v23, v2, s57, v3 bitop3:0xde
	v_bitop3_b32 v24, v2, s58, v3 bitop3:0xde
	v_bitop3_b32 v25, v2, s59, v3 bitop3:0xde
	v_lshl_add_u64 v[2:3], s[40:41], 0, v[0:1]
	v_lshlrev_b64 v[4:5], 1, v[4:5]
	v_lshl_add_u64 v[132:133], v[2:3], 0, v[4:5]
	v_add_u32_e32 v2, v19, v13
	v_lshl_or_b32 v8, v17, 5, v12
	v_lshlrev_b32_e32 v9, 6, v18
	v_ashrrev_i32_e32 v3, 31, v2
	v_sub_u32_e32 v8, v8, v9
	v_lshlrev_b64 v[2:3], 11, v[2:3]
	v_ashrrev_i32_e32 v9, 31, v8
	v_lshl_add_u64 v[0:1], s[50:51], 0, v[0:1]
	s_waitcnt vmcnt(6)
	v_lshlrev_b32_e32 v143, 6, v20
	v_lshlrev_b32_e32 v20, 13, v20
	v_lshlrev_b64 v[8:9], 1, v[8:9]
	v_lshl_add_u64 v[136:137], v[0:1], 0, v[4:5]
	v_lshl_add_u64 v[0:1], s[50:51], 0, v[2:3]
	v_or_b32_e32 v26, 0x800, v20
	v_or_b32_e32 v27, 0x1000, v20
	v_or_b32_e32 v28, 0x1800, v20
	v_lshl_add_u64 v[6:7], s[40:41], 0, v[2:3]
	v_lshl_add_u64 v[138:139], v[0:1], 0, v[8:9]
	v_mov_b32_e32 v0, 0
	v_lshrrev_b32_e32 v142, 6, v141
	v_lshl_add_u64 v[134:135], v[6:7], 0, v[8:9]
	s_mov_b32 s37, -2
	v_add_u32_e32 v167, v21, v10
	v_add_u32_e32 v150, v11, v20
	v_add_u32_e32 v149, v22, v26
	v_add_u32_e32 v148, v22, v27
	v_add_u32_e32 v147, v22, v28
	v_add_u32_e32 v166, 0xc000, v144
	v_add_u32_e32 v165, 0xe000, v144
	v_add_u32_e32 v164, v23, v10
	v_add_u32_e32 v155, v24, v10
	v_add_u32_e32 v152, v25, v10
	v_mov_b32_e32 v1, v0
	v_mov_b32_e32 v2, v0
	v_mov_b32_e32 v3, v0
	v_mov_b32_e32 v4, v0
	v_mov_b32_e32 v5, v0
	v_mov_b32_e32 v6, v0
	v_mov_b32_e32 v7, v0
	v_mov_b32_e32 v12, v0
	v_mov_b32_e32 v13, v0
	v_mov_b32_e32 v14, v0
	v_mov_b32_e32 v15, v0
	v_mov_b32_e32 v20, v0
	v_mov_b32_e32 v21, v0
	v_mov_b32_e32 v22, v0
	v_mov_b32_e32 v23, v0
	v_mov_b32_e32 v8, v0
	v_mov_b32_e32 v9, v0
	v_mov_b32_e32 v10, v0
	v_mov_b32_e32 v11, v0
	v_mov_b32_e32 v16, v0
	v_mov_b32_e32 v17, v0
	v_mov_b32_e32 v18, v0
	v_mov_b32_e32 v19, v0
	v_mov_b32_e32 v28, v0
	v_mov_b32_e32 v29, v0
	v_mov_b32_e32 v30, v0
	v_mov_b32_e32 v31, v0
	v_mov_b32_e32 v36, v0
	v_mov_b32_e32 v37, v0
	v_mov_b32_e32 v38, v0
	v_mov_b32_e32 v39, v0
	v_mov_b32_e32 v24, v0
	v_mov_b32_e32 v25, v0
	v_mov_b32_e32 v26, v0
	v_mov_b32_e32 v27, v0
	v_mov_b32_e32 v32, v0
	v_mov_b32_e32 v33, v0
	v_mov_b32_e32 v34, v0
	v_mov_b32_e32 v35, v0
	v_mov_b32_e32 v44, v0
	v_mov_b32_e32 v45, v0
	v_mov_b32_e32 v46, v0
	v_mov_b32_e32 v47, v0
	v_mov_b32_e32 v52, v0
	v_mov_b32_e32 v53, v0
	v_mov_b32_e32 v54, v0
	v_mov_b32_e32 v55, v0
	v_mov_b32_e32 v40, v0
	v_mov_b32_e32 v41, v0
	v_mov_b32_e32 v42, v0
	v_mov_b32_e32 v43, v0
	v_mov_b32_e32 v48, v0
	v_mov_b32_e32 v49, v0
	v_mov_b32_e32 v50, v0
	v_mov_b32_e32 v51, v0
	v_mov_b32_e32 v56, v0
	v_mov_b32_e32 v57, v0
	v_mov_b32_e32 v58, v0
	v_mov_b32_e32 v59, v0
	v_mov_b32_e32 v60, v0
	v_mov_b32_e32 v61, v0
	v_mov_b32_e32 v62, v0
	v_mov_b32_e32 v63, v0
	v_mov_b32_e32 v64, v0
	v_mov_b32_e32 v65, v0
	v_mov_b32_e32 v66, v0
	v_mov_b32_e32 v67, v0
	v_mov_b32_e32 v68, v0
	v_mov_b32_e32 v69, v0
	v_mov_b32_e32 v70, v0
	v_mov_b32_e32 v71, v0
	v_mov_b32_e32 v80, v0
	v_mov_b32_e32 v81, v0
	v_mov_b32_e32 v82, v0
	v_mov_b32_e32 v83, v0
	v_mov_b32_e32 v88, v0
	v_mov_b32_e32 v89, v0
	v_mov_b32_e32 v90, v0
	v_mov_b32_e32 v91, v0
	v_mov_b32_e32 v72, v0
	v_mov_b32_e32 v73, v0
	v_mov_b32_e32 v74, v0
	v_mov_b32_e32 v75, v0
	v_mov_b32_e32 v76, v0
	v_mov_b32_e32 v77, v0
	v_mov_b32_e32 v78, v0
	v_mov_b32_e32 v79, v0
	v_mov_b32_e32 v96, v0
	v_mov_b32_e32 v97, v0
	v_mov_b32_e32 v98, v0
	v_mov_b32_e32 v99, v0
	v_mov_b32_e32 v104, v0
	v_mov_b32_e32 v105, v0
	v_mov_b32_e32 v106, v0
	v_mov_b32_e32 v107, v0
	v_mov_b32_e32 v84, v0
	v_mov_b32_e32 v85, v0
	v_mov_b32_e32 v86, v0
	v_mov_b32_e32 v87, v0
	v_mov_b32_e32 v92, v0
	v_mov_b32_e32 v93, v0
	v_mov_b32_e32 v94, v0
	v_mov_b32_e32 v95, v0
	v_mov_b32_e32 v112, v0
	v_mov_b32_e32 v113, v0
	v_mov_b32_e32 v114, v0
	v_mov_b32_e32 v115, v0
	v_mov_b32_e32 v116, v0
	v_mov_b32_e32 v117, v0
	v_mov_b32_e32 v118, v0
	v_mov_b32_e32 v119, v0
	v_mov_b32_e32 v100, v0
	v_mov_b32_e32 v101, v0
	v_mov_b32_e32 v102, v0
	v_mov_b32_e32 v103, v0
	v_mov_b32_e32 v108, v0
	v_mov_b32_e32 v109, v0
	v_mov_b32_e32 v110, v0
	v_mov_b32_e32 v111, v0
	v_mov_b32_e32 v120, v0
	v_mov_b32_e32 v121, v0
	v_mov_b32_e32 v122, v0
	v_mov_b32_e32 v123, v0
	v_mov_b32_e32 v124, v0
	v_mov_b32_e32 v125, v0
	v_mov_b32_e32 v126, v0
	v_mov_b32_e32 v127, v0
	s_movk_i32 s98, 0x100
	v_cmp_gt_u32_e64 s[100:101], s98, v220
	s_and_saveexec_b64 s[98:99], s[100:101]
	v_mul_f32_e32 v221, 0x3a800000, v221
	v_add_f32_e32 v221, 0x358637bd, v221
	v_rsq_f32_e32 v221, v221
	ds_write_b32 v223, v221
	s_or_b64 exec, exec, s[98:99]
	s_barrier

; __global__ void __launch_bounds__(NTHR) fwd_megakernel(Params p) {
	.amdhsa_kernel _Z14fwd_megakernel6Params
		.amdhsa_group_segment_fixed_size 133120
		.amdhsa_private_segment_fixed_size 0
		.amdhsa_kernarg_size 400
		.amdhsa_user_sgpr_count 2
		.amdhsa_user_sgpr_dispatch_ptr 0
		.amdhsa_user_sgpr_queue_ptr 0
		.amdhsa_user_sgpr_kernarg_segment_ptr 1
		.amdhsa_user_sgpr_dispatch_id 0
		.amdhsa_user_sgpr_kernarg_preload_length 0
		.amdhsa_user_sgpr_kernarg_preload_offset 0
		.amdhsa_user_sgpr_private_segment_size 0
		.amdhsa_uses_dynamic_stack 0
		.amdhsa_enable_private_segment 0
		.amdhsa_system_sgpr_workgroup_id_x 1
		.amdhsa_system_sgpr_workgroup_id_y 0
		.amdhsa_system_sgpr_workgroup_id_z 0
		.amdhsa_system_sgpr_workgroup_info 0
		.amdhsa_system_vgpr_workitem_id 2
		.amdhsa_next_free_vgpr 256
		.amdhsa_next_free_sgpr 102
		.amdhsa_accum_offset 256
		.amdhsa_reserve_vcc 1
		.amdhsa_float_round_mode_32 0
		.amdhsa_float_round_mode_16_64 0
		.amdhsa_float_denorm_mode_32 3
		.amdhsa_float_denorm_mode_16_64 3
		.amdhsa_dx10_clamp 1
		.amdhsa_ieee_mode 1
		.amdhsa_fp16_overflow 0
		.amdhsa_tg_split 0
		.amdhsa_exception_fp_ieee_invalid_op 0
		.amdhsa_exception_fp_denorm_src 0
		.amdhsa_exception_fp_ieee_div_zero 0
		.amdhsa_exception_fp_ieee_overflow 0
		.amdhsa_exception_fp_ieee_underflow 0
		.amdhsa_exception_fp_ieee_inexact 0
		.amdhsa_exception_int_div_zero 0
	.end_amdhsa_kernel

; __global__ void __launch_bounds__(NTHR) fwd_megakernel(Params p) {
amdhsa.kernels:
  - .agpr_count:     0
    .args:
      - .offset:         0
        .size:           144
        .value_kind:     by_value
      - .offset:         144
        .size:           4
        .value_kind:     hidden_block_count_x
      - .offset:         148
        .size:           4
        .value_kind:     hidden_block_count_y
      - .offset:         152
        .size:           4
        .value_kind:     hidden_block_count_z
      - .offset:         156
        .size:           2
        .value_kind:     hidden_group_size_x
      - .offset:         158
        .size:           2
        .value_kind:     hidden_group_size_y
      - .offset:         160
        .size:           2
        .value_kind:     hidden_group_size_z
      - .offset:         162
        .size:           2
        .value_kind:     hidden_remainder_x
      - .offset:         164
        .size:           2
        .value_kind:     hidden_remainder_y
      - .offset:         166
        .size:           2
        .value_kind:     hidden_remainder_z
      - .offset:         184
        .size:           8
        .value_kind:     hidden_global_offset_x
      - .offset:         192
        .size:           8
        .value_kind:     hidden_global_offset_y
      - .offset:         200
        .size:           8
        .value_kind:     hidden_global_offset_z
      - .offset:         208
        .size:           2
        .value_kind:     hidden_grid_dims
      - .offset:         232
        .size:           8
        .value_kind:     hidden_multigrid_sync_arg
    .group_segment_fixed_size: 133120
    .kernarg_segment_align: 8
    .kernarg_segment_size: 400
    .language:       OpenCL C
    .language_version:
      - 2
      - 0
    .max_flat_workgroup_size: 512
    .name:           _Z14fwd_megakernel6Params
    .private_segment_fixed_size: 0
    .sgpr_count:     108
    .sgpr_spill_count: 4
    .symbol:         _Z14fwd_megakernel6Params.kd
    .uniform_work_group_size: 1
    .uses_dynamic_stack: false
    .vgpr_count:     256
    .vgpr_spill_count: 0
    .wavefront_size: 64
